# m0 save/restore removed around the attention LDS-DMA issues (nothing else reads m0)
# baseline (speedup 1.0000x reference)
; template<int MODE,int THRL> __device__ __forceinline__ void attn_unit(const bf16*Qw0,int PQ,const bf16*__restrict__ Kh,int PK,const bf16*__restrict__ Vh,int PV,bf16*Ow0,int PO,int NT,int nabase,int nar0,const float*rpbh,char*shm,int&rot,bool pre,bool hasn,long dKn,long dVn){
;     ...
;   int tid_=threadIdx.x; asm volatile("":"+v"(tid_));
;   const int tid=tid_,lane=tid&63,r32=lane&31,hi=lane>>5; const int wid=__builtin_amdgcn_readfirstlane(tid>>6);
;   const bf16*Qw=Qw0+(long)wid*QBLK*PQ;
;   const unsigned lds0=(unsigned)(uintptr_t)shm;
;   float*wsf=(float*)(shm+LDS_WS)+wid*64;
;   const bf16*ksrc=Kh+(long)lane*PK+wid*8;
;   const bf16*vsrc=Vh+(long)(16*(wid&3)+(lane>>2))*PV+(wid>>2)*32+(lane&3)*8;
;   const unsigned kdst=lds0+LDS_K+wid*1024, vdst=lds0+LDS_V+wid*1024;
;     ...
;   const int vb0=(int)(lds0+LDS_V)+((lane>>4)&1)*32+(lane&3)*8+(4*hi+((lane&15)>>2))*64;
;   const char*Kbase=shm+LDS_K; bf16x8 kf[8];
;   const lds_cptr shm3=(lds_cptr)shm; const lds_cptr kp0=shm3+LDS_K+hi*1024+r32*16; const lds_cptr vp0=shm3+LDS_V+((lane>>4)&1)*32+(lane&3)*8+(4*hi+((lane&15)>>2))*64;
;   const lds_cfptr tb=(lds_cfptr)(shm3+LDS_TB);
;   u32x4_t mf[4];
;   const int nar=nar0+(wid>>1), nac=(wid&1)*32+r32;
;   if(!pre){ DMA_K(0,rot);DMA_V(0,rot);DMA_K(1,NXT(rot)); }
; template <int l> __device__ __forceinline__ void layer_body(const Args& a, unsigned char* lds, const XcdBarrier& bar, int G, int bx, int vcu, int gw, int NGW, int lane_, int tid_k, int wave) {
;     ...
;                 for (int i = 0; i < pern; ++i) { const int n = vcu * pern + i; if (n >= 1024) break;
;                     const int b = n >> 8, h = (n >> 5) & 7, qb = n & 31; const int r0 = qb * 4; int nb = r0 - 4; nb = nb < 0 ? 0 : (nb > 116 ? 116 : nb);
;                     const size_t rb = (size_t)b * TPB, rq = rb + CTXL + (size_t)qb * 256;
;                     const int n2 = n + 1; const bool hasn = (i + 1 < pern) && (n2 < 1024); const int b2 = n2 >> 8, h2 = (n2 >> 5) & 7; const size_t rb2 = (size_t)b2 * TPB;
;                     attn_body::attn_unit<1, 8>(qkv + rq * PAR_IN + h * 64, PAR_IN, qkv + rb * PAR_IN + 512 + h * 64, PAR_IN, qkv + rb * PAR_IN + 1024 + h * 64, PAR_IN,
;                                                (abf*)AO + rq * DMODEL + h * 64, DMODEL, 16, nb, r0, (const float*)(ws + WS_MF) + (size_t)h * (15 * 2 * 64 * 16), (char*)lds,
.LBB0_317:
	s_add_i32 s77, s75, s1
	s_cmpk_gt_i32 s77, 0x3ff
	s_mov_b64 s[4:5], -1
	s_cbranch_scc1 .LBB0_316
	s_ashr_i32 s15, s77, 8
	s_mul_hi_i32 s61, s15, 0x1290000
	s_mul_i32 s60, s15, 0x1290000
	s_xor_b64 s[4:5], s[62:63], -1
	s_bfe_u32 s13, s77, 0x30005
	s_lshl_b64 s[56:57], s[60:61], 1
	s_add_u32 s3, s44, s56
	s_addc_u32 s6, s45, s57
	s_lshl_b32 s12, s13, 7
	v_mov_b32_e32 v34, v222
	s_add_u32 s58, s3, s12
	s_addc_u32 s59, s6, 0
	v_and_b32_e32 v234, 63, v34
	v_readfirstlane_b32 s3, v34
	s_ashr_i32 s56, s3, 6
	v_mul_u32_u24_e32 v1, 0x900, v234
	v_lshlrev_b32_e32 v2, 1, v1
	s_lshl_b32 s6, s56, 4
	v_bfe_u32 v1, v34, 2, 4
	v_mov_b32_e32 v3, v0
	s_lshl_b32 s62, s56, 3
	v_and_or_b32 v1, s6, 48, v1
	v_lshl_add_u64 v[2:3], s[58:59], 0, v[2:3]
	s_ashr_i32 s63, s62, 31
	v_mul_u32_u24_e32 v1, 0x900, v1
	v_lshl_add_u64 v[226:227], s[62:63], 1, v[2:3]
	v_lshlrev_b32_e32 v2, 1, v1
	v_mov_b32_e32 v3, v0
	s_ashr_i32 s6, s3, 3
	v_lshl_add_u64 v[2:3], s[58:59], 0, v[2:3]
	s_and_b32 s58, s6, 0xffffffe0
	v_lshlrev_b32_e32 v235, 3, v34
	s_ashr_i32 s59, s58, 31
	v_and_b32_e32 v238, 24, v235
	v_lshl_add_u64 v[2:3], s[58:59], 1, v[2:3]
	v_lshlrev_b32_e32 v4, 1, v238
	v_mov_b32_e32 v5, v0
	v_lshl_add_u64 v[182:183], v[2:3], 0, v[4:5]
	s_lshl_b32 s78, s56, 10
	v_lshl_add_u64 v[214:215], v[226:227], 0, s[8:9]
	v_lshl_add_u64 v[228:229], v[182:183], 0, s[10:11]
	s_add_i32 s79, s78, 0x6000
	s_mov_b64 s[58:59], -1
	s_and_b64 vcc, exec, s[4:5]
	s_cbranch_vccz .LBB0_320
	s_add_i32 s6, s78, s14
	s_mov_b32 m0, s6
	s_nop 0
	global_load_lds_dwordx4 v[214:215], off
	s_lshl_b32 s6, s14, 1
	s_add_i32 s6, s79, s6
	s_add_i32 s57, s14, 0x2000
	s_cmpk_lg_i32 s14, 0x4000
	s_mov_b32 m0, s6
	s_nop 0
	global_load_lds_dwordx4 v[228:229], off
	s_cselect_b32 s6, s57, 0
	v_lshl_add_u64 v[2:3], v[214:215], 0, s[48:49]
	s_add_i32 s6, s78, s6
	s_mov_b32 m0, s6
	s_nop 0
	global_load_lds_dwordx4 v[2:3], off
	s_mov_b64 s[58:59], 0

; #define WAIT_BAR(N) asm volatile("s_waitcnt vmcnt(" #N ") lgkmcnt(0)\n\ts_barrier":::"memory")
;   #define DMA_K(t,slot) glds16(ksrc+(long)KROW(t)*PK,(unsigned)__builtin_amdgcn_readfirstlane(kdst+(slot)))
; template<int MODE,int THRL> __device__ __forceinline__ void attn_unit(const bf16*Qw0,int PQ,const bf16*__restrict__ Kh,int PK,const bf16*__restrict__ Vh,int PV,bf16*Ow0,int PO,int NT,int nabase,int nar0,const float*rpbh,char*shm,int&rot,bool pre,bool hasn,long dKn,long dVn){
;     ...
;   bf16x8 qr[4];
;   #pragma unroll
;   for(int d0=0;d0<4;++d0)qr[d0]=*reinterpret_cast<const bf16x8*>(&Qw[(long)r32*PQ+d0*16+hi*8]);
;   float mhat=0.f,l_reg=0.f;constexpr int ND=(MODE==2)?4:2; f32x16 o[4];o[0]=f32x16{};o[1]=f32x16{};o[2]=f32x16{};o[3]=f32x16{};f32x16 negm=f32x16{};asm volatile("":"+v"(negm));
;     ...
;   bool resc=false;
;     ...
;   f32x16 pA0,pA1,pB0,pB1;
;   int sl_prev=rot,sl_cur=rot,sl_next=NXT(rot);
;   bool pfnow=false;
;     ...
;   if(!pre){ DMA_K(2,NXT(sl_next)); }
;   if(pre){WAIT_BAR(0);}else if(MODE==2){WAIT_BAR(4);}else{WAIT_BAR(3);}
.LBB0_322:
	s_and_b32 s12, s77, 31
	s_lshl_b32 s6, s13, 6
	s_mul_hi_i32 s58, s15, 0x2100
	s_mulk_i32 s15, 0x2100
	s_lshl_b32 s59, s12, 8
	s_add_u32 s15, s15, s59
	s_addc_u32 s59, s58, 0
	s_add_u32 s58, s15, 0x100
	s_addc_u32 s59, s59, 0
	s_mul_i32 s15, s59, 0x1200
	s_mul_hi_u32 s62, s58, 0x1200
	s_add_i32 s62, s62, s15
	s_mul_i32 s15, s58, 0x1200
	s_add_u32 s15, s44, s15
	s_addc_u32 s62, s45, s62
	s_lshl_b32 s76, s6, 1
	s_add_u32 s15, s15, s76
	v_and_b32_e32 v236, 31, v34
	s_addc_u32 s63, s62, 0
	s_mul_i32 s62, s56, 0x24000
	v_mul_u32_u24_e32 v1, 0x900, v236
	v_lshrrev_b32_e32 v237, 5, v234
	s_mul_hi_i32 s64, s56, 0x24000
	s_add_u32 s62, s15, s62
	v_lshlrev_b32_e32 v1, 1, v1
	s_addc_u32 s63, s63, s64
	v_lshl_or_b32 v1, v237, 4, v1
	global_load_dwordx4 v[142:145], v1, s[62:63]
	global_load_dwordx4 v[138:141], v1, s[62:63] offset:32
	global_load_dwordx4 v[134:137], v1, s[62:63] offset:64
	global_load_dwordx4 v[130:133], v1, s[62:63] offset:96
	v_mov_b32_e32 v2, v0
	v_mov_b32_e32 v3, v0
	v_mov_b32_e32 v4, v0
	v_mov_b32_e32 v5, v0
	v_mov_b32_e32 v6, v0
	v_mov_b32_e32 v7, v0
	v_mov_b32_e32 v8, v0
	v_mov_b32_e32 v9, v0
	v_mov_b32_e32 v10, v0
	v_mov_b32_e32 v11, v0
	v_mov_b32_e32 v12, v0
	v_mov_b32_e32 v13, v0
	v_mov_b32_e32 v14, v0
	v_mov_b32_e32 v15, v0
	v_mov_b32_e32 v1, v0
	v_mov_b64_e32 v[16:17], v[14:15]
	s_cmpk_lg_i32 s14, 0x4000
	v_mov_b64_e32 v[14:15], v[12:13]
	v_mov_b64_e32 v[12:13], v[10:11]
	v_mov_b64_e32 v[10:11], v[8:9]
	v_mov_b64_e32 v[8:9], v[6:7]
	v_mov_b64_e32 v[6:7], v[4:5]
	v_mov_b64_e32 v[4:5], v[2:3]
	v_mov_b64_e32 v[2:3], v[0:1]
	s_cselect_b32 s62, s57, 0
	s_andn2_b64 vcc, exec, s[4:5]
	s_mov_b64 s[4:5], -1
	s_cbranch_vccnz .LBB0_324
	s_add_i32 s57, s62, 0x2000
	s_cmpk_lg_i32 s62, 0x4000
	s_cselect_b32 s4, s57, 0
	v_lshl_add_u64 v[18:19], v[214:215], 0, s[52:53]
	s_add_i32 s4, s4, s78
	s_mov_b32 m0, s4
	s_nop 0
	global_load_lds_dwordx4 v[18:19], off
	s_waitcnt vmcnt(3) lgkmcnt(0)
	s_barrier
	s_mov_b64 s[4:5], 0

; #define WAIT_BAR(N) asm volatile("s_waitcnt vmcnt(" #N ") lgkmcnt(0)\n\ts_barrier":::"memory")
;   #define DMA_K(t,slot) glds16(ksrc+(long)KROW(t)*PK,(unsigned)__builtin_amdgcn_readfirstlane(kdst+(slot)))
;   #define DMA_V(t,slot) do{ glds16(vsrc+(long)KROW(t)*PV,(unsigned)__builtin_amdgcn_readfirstlane(vdst+2*(slot))); if(MODE==2)glds16(vsrc+(long)KROW(t)*PV+64,(unsigned)__builtin_amdgcn_readfirstlane(vdst+2*(slot)+SLOTB)); }while(0)
;   #define CMASK(P0,P1,t) do{ if(MODE==1&&(t)>=4)na_apply(P0,P1,mf,na_rowok((t),nabase,nar)); }while(0)
;   #define START(P0,P1) do{ const float rm=rowmax(P0,P1); resc=false; \
;     { const float dl=rm; mhat=fadd_s(mhat,dl); \
;       _Pragma("unroll") for(int r=0;r<16;++r){P0[r]=fsub_s(P0[r],dl);P1[r]=fsub_s(P1[r],dl);} \
;       _Pragma("unroll") for(int r=0;r<16;++r)negm[r]=-mhat; asm volatile("":"+v"(negm)); } \
;     _Pragma("unroll") for(int r=0;r<16;++r)P0[r]=__builtin_amdgcn_exp2f(P0[r]); }while(0)
;   #define ROT() do{sl_prev=sl_cur;sl_cur=sl_next;sl_next=(sl_next==(NSLOT-1)*SLOTB)?0:sl_next+SLOTB;}while(0)
; template<int MODE,int THRL> __device__ __forceinline__ void attn_unit(const bf16*Qw0,int PQ,const bf16*__restrict__ Kh,int PK,const bf16*__restrict__ Vh,int PV,bf16*Ow0,int PO,int NT,int nabase,int nar0,const float*rpbh,char*shm,int&rot,bool pre,bool hasn,long dKn,long dVn){
;     ...
;   f32x16 pA0,pA1,pB0,pB1;
;   int sl_prev=rot,sl_cur=rot,sl_next=NXT(rot);
;   bool pfnow=false;
;     ...
;   if(!pre){ DMA_K(2,NXT(sl_next)); }
;   if(pre){WAIT_BAR(0);}else if(MODE==2){WAIT_BAR(4);}else{WAIT_BAR(3);}
;   qkt(pA0,pA1,Kbase+sl_cur,qr,negm,r32,hi);asm volatile("s_nop 15\n\ts_nop 7":"+v"(pA0),"+v"(pA1));CMASK(pA0,pA1,0);
;   START(pA0,pA1);
;   _Pragma("unroll") for(int r=0;r<16;++r)pA1[r]=__builtin_amdgcn_exp2f(pA1[r]);
;   WAIT_BAR(0);
;   DMA_K(3,sl_cur);DMA_V(1,sl_next);
;   ROT();
;   kload8(kf,kp0+sl_cur);
;   if(MODE==2){WAIT_BAR(3);}else{WAIT_BAR(2);}
.LBB0_326:
	v_lshlrev_b32_e32 v35, 10, v237
	v_lshlrev_b32_e32 v48, 4, v236
	v_add3_u32 v1, s14, v35, v48
	ds_read_b128 v[36:39], v1
	ds_read_b128 v[40:43], v1 offset:512
	s_lshl_b32 s12, s12, 2
	v_or_b32_e32 v244, v35, v48
	s_waitcnt vmcnt(3) lgkmcnt(1)
	v_mfma_f32_32x32x16_bf16 v[18:33], v[36:39], v[142:145], v[2:17]
	s_and_b32 s4, s3, 0x3fffffc0
	s_lshl_b32 s67, s4, 2
	s_add_i32 s4, s78, s14
	s_lshl_b32 s70, s62, 1
	v_lshl_add_u64 v[206:207], v[228:229], 0, s[48:49]
	s_add_i32 s67, s67, 0x12000
	v_lshl_or_b32 v240, v236, 2, s67
	s_waitcnt lgkmcnt(0)
	v_mfma_f32_32x32x16_bf16 v[2:17], v[40:43], v[142:145], v[2:17]
	ds_read_b128 v[36:39], v1 offset:2048
	ds_read_b128 v[40:43], v1 offset:2560
	s_waitcnt vmcnt(2) lgkmcnt(1)
	v_mfma_f32_32x32x16_bf16 v[18:33], v[36:39], v[138:141], v[18:33]
	s_waitcnt lgkmcnt(0)
	v_mfma_f32_32x32x16_bf16 v[2:17], v[40:43], v[138:141], v[2:17]
	ds_read_b128 v[36:39], v1 offset:4096
	ds_read_b128 v[40:43], v1 offset:4608
	s_waitcnt vmcnt(1) lgkmcnt(1)
	v_mfma_f32_32x32x16_bf16 v[18:33], v[36:39], v[134:137], v[18:33]
	ds_read_b128 v[36:39], v1 offset:6656
	ds_read_b128 v[44:47], v1 offset:6144
	v_med3_u32 v1, s12, 4, v232
	s_nop 0
	v_readfirstlane_b32 s80, v1
	v_lshlrev_b32_e32 v1, 1, v34
	v_and_b32_e32 v239, 32, v1
	v_lshlrev_b32_e32 v1, 4, v34
	s_waitcnt lgkmcnt(2)
	v_mfma_f32_32x32x16_bf16 v[2:17], v[40:43], v[134:137], v[2:17]
	s_lshl_b32 s15, s80, 6
	v_and_b32_e32 v1, 0xc0, v1
	v_lshl_or_b32 v1, v237, 8, v1
	v_or3_b32 v243, v239, v238, v1
	s_waitcnt vmcnt(0) lgkmcnt(0)
	v_mfma_f32_32x32x16_bf16 v[18:33], v[44:47], v[130:133], v[18:33]
	v_mfma_f32_32x32x16_bf16 v[2:17], v[36:39], v[130:133], v[2:17]
	s_nop 15
	s_nop 7
	s_nop 0
	v_max3_f32 v34, v18, v19, v2
	v_max3_f32 v35, v20, v21, v3
	s_nop 0
	v_max3_f32 v34, v34, v4, v5
	v_max3_f32 v35, v35, v24, v25
	s_nop 0
	v_max3_f32 v34, v34, v22, v23
	v_max3_f32 v35, v35, v8, v9
	s_nop 0
	v_max3_f32 v34, v34, v6, v7
	v_max3_f32 v35, v35, v28, v29
	s_nop 0
	v_max3_f32 v34, v34, v26, v27
	v_max3_f32 v35, v35, v12, v13
	s_nop 0
	v_max3_f32 v34, v34, v10, v11
	v_max3_f32 v35, v35, v32, v33
	s_nop 0
	v_max3_f32 v34, v34, v30, v31
	v_max3_f32 v35, v35, v16, v17
	s_nop 0
	v_max3_f32 v34, v34, v14, v15
	s_nop 0
	v_max_f32_e32 v34, v34, v35
	s_nop 0
	v_mov_b32_e32 v35, v34
	s_nop 1
	v_permlane32_swap_b32_e32 v34, v35
	v_max_f32_e32 v34, v34, v35
	s_nop 0
	v_add_f32_e32 v241, v0, v34
	v_sub_f32_e32 v18, v18, v34
	v_sub_f32_e32 v2, v2, v34
	v_sub_f32_e32 v19, v19, v34
	v_sub_f32_e32 v3, v3, v34
	v_sub_f32_e32 v20, v20, v34
	v_sub_f32_e32 v4, v4, v34
	v_sub_f32_e32 v21, v21, v34
	v_sub_f32_e32 v5, v5, v34
	v_sub_f32_e32 v22, v22, v34
	v_sub_f32_e32 v6, v6, v34
	v_sub_f32_e32 v23, v23, v34
	v_sub_f32_e32 v7, v7, v34
	v_sub_f32_e32 v24, v24, v34
	v_sub_f32_e32 v8, v8, v34
	v_sub_f32_e32 v25, v25, v34
	v_sub_f32_e32 v9, v9, v34
	v_sub_f32_e32 v26, v26, v34
	v_sub_f32_e32 v10, v10, v34
	v_sub_f32_e32 v27, v27, v34
	v_sub_f32_e32 v11, v11, v34
	v_sub_f32_e32 v28, v28, v34
	v_sub_f32_e32 v12, v12, v34
	v_sub_f32_e32 v29, v29, v34
	v_sub_f32_e32 v13, v13, v34
	v_sub_f32_e32 v30, v30, v34
	v_sub_f32_e32 v14, v14, v34
	v_sub_f32_e32 v31, v31, v34
	v_sub_f32_e32 v15, v15, v34
	v_sub_f32_e32 v32, v32, v34
	v_sub_f32_e32 v16, v16, v34
	v_sub_f32_e32 v33, v33, v34
	v_sub_f32_e32 v17, v17, v34
	s_nop 0
	v_xor_b32_e32 v34, 0x80000000, v241
	v_mov_b32_e32 v35, v34
	v_mov_b32_e32 v36, v34
	v_mov_b32_e32 v37, v34
	v_mov_b32_e32 v38, v34
	v_mov_b32_e32 v39, v34
	v_mov_b32_e32 v40, v34
	v_mov_b32_e32 v41, v34
	v_mov_b32_e32 v42, v34
	v_mov_b32_e32 v43, v34
	v_mov_b32_e32 v44, v34
	v_mov_b32_e32 v45, v34
	v_mov_b32_e32 v46, v34
	v_mov_b32_e32 v47, v34
	v_mov_b32_e32 v48, v34
	v_mov_b32_e32 v49, v34
	s_waitcnt vmcnt(0) lgkmcnt(0)
	s_barrier
	v_exp_f32_e32 v112, v2
	v_exp_f32_e32 v113, v3
	v_lshl_add_u64 v[2:3], v[214:215], 0, s[54:55]
	s_mov_b32 m0, s4
	s_nop 0
	global_load_lds_dwordx4 v[2:3], off
	s_add_i32 s4, s70, s79
	s_mov_b32 m0, s4
	s_nop 0
	global_load_lds_dwordx4 v[206:207], off
	v_add_u32_e32 v2, s62, v244
	v_exp_f32_e32 v50, v22
	v_exp_f32_e32 v51, v23
	v_exp_f32_e32 v70, v24
	v_exp_f32_e32 v71, v25
	v_exp_f32_e32 v72, v26
	v_exp_f32_e32 v73, v27
	v_exp_f32_e32 v74, v28
	v_exp_f32_e32 v75, v29
	v_exp_f32_e32 v92, v30
	v_exp_f32_e32 v93, v31
	v_exp_f32_e32 v94, v32
	v_exp_f32_e32 v95, v33
	v_exp_f32_e32 v116, v6
	v_exp_f32_e32 v117, v7
	v_exp_f32_e32 v146, v8
	v_exp_f32_e32 v147, v9
	v_exp_f32_e32 v148, v10
	v_exp_f32_e32 v149, v11
	v_exp_f32_e32 v150, v12
	v_exp_f32_e32 v151, v13
	v_exp_f32_e32 v152, v14
	v_exp_f32_e32 v153, v15
	v_exp_f32_e32 v154, v16
	v_exp_f32_e32 v155, v17
	ds_read_b128 v[6:9], v2
	ds_read_b128 v[10:13], v2 offset:512
	ds_read_b128 v[14:17], v2 offset:2048
	ds_read_b128 v[22:25], v2 offset:2560
	ds_read_b128 v[26:29], v2 offset:4096
	ds_read_b128 v[30:33], v2 offset:4608
	ds_read_b128 v[66:69], v2 offset:6144
	ds_read_b128 v[108:111], v2 offset:6656
	v_exp_f32_e32 v18, v18
	v_exp_f32_e32 v19, v19
	v_exp_f32_e32 v20, v20
	v_exp_f32_e32 v21, v21
	v_exp_f32_e32 v114, v4
	v_exp_f32_e32 v115, v5
	s_waitcnt vmcnt(2) lgkmcnt(0)
	s_barrier
	s_cmpk_lg_i32 s62, 0x4000
	s_cselect_b32 s57, s57, 0
	v_cmp_gt_u32_e64 s[4:5], 32, v234
	v_lshl_add_u32 v156, s14, 1, v243
	ds_read_b64_tr_b16 v[2:3], v156 offset:24576
	ds_read_b64_tr_b16 v[4:5], v156 offset:25088
	s_waitcnt lgkmcnt(9)
	v_mfma_f32_32x32x16_bf16 v[76:91], v[6:9], v[142:145], v[34:49]
	v_add_f32_e32 v52, v18, v19
	v_add_f32_e32 v52, v52, v20
	v_add_f32_e32 v52, v52, v21
	v_add_f32_e32 v52, v52, v50
	v_add_f32_e32 v52, v52, v51
	v_cvt_pk_bf16_f32 v126, v18, v19
	v_cvt_pk_bf16_f32 v127, v20, v21
	ds_read_b64_tr_b16 v[18:19], v156 offset:28672
	ds_read_b64_tr_b16 v[20:21], v156 offset:29184
	v_add_f32_e32 v6, v70, v52
	v_cvt_pk_bf16_f32 v128, v50, v51
	s_waitcnt lgkmcnt(10)
	v_mfma_f32_32x32x16_bf16 v[50:65], v[10:13], v[142:145], v[34:49]
	v_add_f32_e32 v6, v71, v6
	v_add_f32_e32 v6, v72, v6
	v_add_f32_e32 v6, v73, v6
	v_cvt_pk_bf16_f32 v129, v70, v71
	ds_read_b64_tr_b16 v[104:105], v156 offset:25600
	ds_read_b64_tr_b16 v[106:107], v156 offset:26112
	s_waitcnt lgkmcnt(11)
	v_mfma_f32_32x32x16_bf16 v[76:91], v[14:17], v[138:141], v[76:91]
	v_add_f32_e32 v6, v74, v6
	v_add_f32_e32 v6, v75, v6
	v_add_f32_e32 v6, v92, v6
	v_add_f32_e32 v6, v93, v6
	v_cvt_pk_bf16_f32 v122, v72, v73
	v_cvt_pk_bf16_f32 v123, v74, v75
	ds_read_b64_tr_b16 v[100:101], v156 offset:29696
	ds_read_b64_tr_b16 v[102:103], v156 offset:30208
	s_waitcnt lgkmcnt(12)
	v_mfma_f32_32x32x16_bf16 v[50:65], v[22:25], v[138:141], v[50:65]
	v_add_f32_e32 v6, v94, v6
	v_add_f32_e32 v6, v95, v6
	v_add_f32_e32 v6, v112, v6
	v_add_f32_e32 v6, v113, v6
	v_cvt_pk_bf16_f32 v124, v92, v93
	v_cvt_pk_bf16_f32 v125, v94, v95
	ds_read_b64_tr_b16 v[96:97], v156 offset:26624
	ds_read_b64_tr_b16 v[98:99], v156 offset:27136
	s_waitcnt lgkmcnt(13)
	v_mfma_f32_32x32x16_bf16 v[76:91], v[26:29], v[134:137], v[76:91]
	v_add_f32_e32 v6, v114, v6
	v_add_f32_e32 v6, v115, v6
	v_add_f32_e32 v6, v116, v6
	v_add_f32_e32 v6, v117, v6
	v_cvt_pk_bf16_f32 v118, v112, v113
	v_cvt_pk_bf16_f32 v119, v114, v115
	ds_read_b64_tr_b16 v[92:93], v156 offset:30720
	ds_read_b64_tr_b16 v[94:95], v156 offset:31232
	s_waitcnt lgkmcnt(14)
	v_mfma_f32_32x32x16_bf16 v[50:65], v[30:33], v[134:137], v[50:65]
	v_add_f32_e32 v6, v146, v6
	v_add_f32_e32 v6, v147, v6
	v_add_f32_e32 v6, v148, v6
	v_add_f32_e32 v6, v149, v6
	v_cvt_pk_bf16_f32 v120, v116, v117
	v_cvt_pk_bf16_f32 v121, v146, v147
	ds_read_b64_tr_b16 v[70:71], v156 offset:27648
	ds_read_b64_tr_b16 v[72:73], v156 offset:28160
	s_waitcnt lgkmcnt(14)
	v_mfma_f32_32x32x16_bf16 v[76:91], v[66:69], v[130:133], v[76:91]
	v_add_f32_e32 v6, v150, v6
	v_add_f32_e32 v6, v151, v6
	v_add_f32_e32 v6, v152, v6
	v_add_f32_e32 v6, v153, v6
	v_cvt_pk_bf16_f32 v114, v148, v149
	v_cvt_pk_bf16_f32 v115, v150, v151
	ds_read_b64_tr_b16 v[66:67], v156 offset:31744
	ds_read_b64_tr_b16 v[68:69], v156 offset:32256
	v_mfma_f32_32x32x16_bf16 v[50:65], v[108:111], v[130:133], v[50:65]
	v_add_f32_e32 v6, v154, v6
	v_add_f32_e32 v6, v155, v6
	v_cvt_pk_bf16_f32 v116, v152, v153
	v_cvt_pk_bf16_f32 v117, v154, v155
	s_nop 0
	v_add_f32_e32 v184, 0, v6
	v_mad_u64_u32 v[6:7], s[64:65], s15, v233, v[214:215]
	s_add_i32 s14, s62, s78
	s_mov_b32 m0, s14
	s_nop 0
	global_load_lds_dwordx4 v[6:7], off
	v_lshl_add_u64 v[6:7], v[228:229], 0, s[52:53]
	s_lshl_b32 s66, s57, 1
	s_add_i32 s14, s66, s79
	s_mov_b32 m0, s14
	s_nop 0
	global_load_lds_dwordx4 v[6:7], off
	v_max_f32_e32 v6, v76, v77
	v_max3_f32 v7, v78, v79, v51
	v_max3_f32 v6, v6, v50, v52
	v_max3_f32 v6, v6, v53, v80
	v_max3_f32 v7, v7, v82, v83
	v_max3_f32 v6, v6, v81, v54
	v_max3_f32 v7, v7, v56, v57
	v_max3_f32 v6, v6, v55, v84
	v_max3_f32 v7, v7, v86, v87
	v_max3_f32 v6, v6, v85, v58
	v_max3_f32 v7, v7, v60, v61
	v_max3_f32 v6, v6, v59, v88
	v_max3_f32 v7, v7, v90, v91
	v_max3_f32 v6, v6, v89, v62
	v_max3_f32 v7, v7, v64, v65
	v_max3_f32 v6, v6, v63, v7
	v_mov_b32_e32 v7, v6
	s_nop 1
	v_permlane32_swap_b32_e32 v6, v7
	v_max_f32_e32 v6, v6, v7
	v_cmp_lt_f32_e32 vcc, s43, v6
	s_cmp_lg_u64 vcc, 0
	s_cselect_b64 s[62:63], -1, 0
	s_cbranch_vccnz .LBB0_428

.LBB0_329:
	s_add_i32 s14, s15, 0xffffff00
	s_add_i32 s15, s57, 0x2000
	s_cmpk_lg_i32 s57, 0x4000
	s_cselect_b32 s67, s15, 0
	v_add_u32_e32 v96, s70, v243
	ds_read_b64_tr_b16 v[154:155], v96 offset:24576
	ds_read_b64_tr_b16 v[156:157], v96 offset:25088
	s_waitcnt lgkmcnt(9)
	v_mfma_f32_32x32x16_bf16 v[98:113], v[150:153], v[142:145], v[34:49]
	v_add_f32_e32 v66, v76, v77
	v_add_f32_e32 v66, v78, v66
	v_add_f32_e32 v66, v79, v66
	v_add_f32_e32 v66, v80, v66
	v_add_f32_e32 v66, v81, v66
	v_cvt_pk_bf16_f32 v126, v76, v77
	v_cvt_pk_bf16_f32 v127, v78, v79
	ds_read_b64_tr_b16 v[150:151], v96 offset:28672
	ds_read_b64_tr_b16 v[152:153], v96 offset:29184
	v_add_f32_e32 v66, v82, v66
	v_add_f32_e32 v66, v83, v66
	v_add_f32_e32 v66, v84, v66
	v_add_f32_e32 v92, v85, v66
	v_cvt_pk_bf16_f32 v128, v80, v81
	s_waitcnt lgkmcnt(10)
	v_mfma_f32_32x32x16_bf16 v[66:81], v[146:149], v[142:145], v[34:49]
	v_cvt_pk_bf16_f32 v129, v82, v83
	ds_read_b64_tr_b16 v[146:147], v96 offset:25600
	ds_read_b64_tr_b16 v[148:149], v96 offset:26112
	s_waitcnt lgkmcnt(11)
	v_mfma_f32_32x32x16_bf16 v[98:113], v[178:181], v[138:141], v[98:113]
	v_add_f32_e32 v82, v86, v92
	v_add_f32_e32 v82, v87, v82
	v_add_f32_e32 v82, v88, v82
	v_add_f32_e32 v82, v89, v82
	v_cvt_pk_bf16_f32 v122, v84, v85
	v_cvt_pk_bf16_f32 v123, v86, v87
	ds_read_b64_tr_b16 v[92:93], v96 offset:29696
	ds_read_b64_tr_b16 v[94:95], v96 offset:30208
	s_waitcnt lgkmcnt(12)
	v_mfma_f32_32x32x16_bf16 v[66:81], v[170:173], v[138:141], v[66:81]
	v_add_f32_e32 v82, v90, v82
	v_add_f32_e32 v82, v91, v82
	v_add_f32_e32 v82, v50, v82
	v_add_f32_e32 v82, v51, v82
	v_cvt_pk_bf16_f32 v124, v88, v89
	v_cvt_pk_bf16_f32 v125, v90, v91
	ds_read_b64_tr_b16 v[86:87], v96 offset:26624
	ds_read_b64_tr_b16 v[88:89], v96 offset:27136
	s_waitcnt lgkmcnt(13)
	v_mfma_f32_32x32x16_bf16 v[98:113], v[174:177], v[134:137], v[98:113]
	v_add_f32_e32 v82, v52, v82
	v_add_f32_e32 v82, v53, v82
	v_add_f32_e32 v82, v54, v82
	v_add_f32_e32 v90, v55, v82
	v_cvt_pk_bf16_f32 v118, v50, v51
	v_cvt_pk_bf16_f32 v119, v52, v53
	ds_read_b64_tr_b16 v[82:83], v96 offset:30720
	ds_read_b64_tr_b16 v[84:85], v96 offset:31232
	s_waitcnt lgkmcnt(14)
	v_mfma_f32_32x32x16_bf16 v[66:81], v[162:165], v[134:137], v[66:81]
	v_add_f32_e32 v50, v56, v90
	v_add_f32_e32 v50, v57, v50
	v_add_f32_e32 v50, v58, v50
	v_add_f32_e32 v50, v59, v50
	v_cvt_pk_bf16_f32 v120, v54, v55
	v_cvt_pk_bf16_f32 v121, v56, v57
	ds_read_b64_tr_b16 v[54:55], v96 offset:27648
	ds_read_b64_tr_b16 v[56:57], v96 offset:28160
	s_waitcnt lgkmcnt(14)
	v_mfma_f32_32x32x16_bf16 v[98:113], v[166:169], v[130:133], v[98:113]
	v_add_f32_e32 v50, v60, v50
	v_add_f32_e32 v50, v61, v50
	v_add_f32_e32 v50, v62, v50
	v_add_f32_e32 v90, v63, v50
	v_cvt_pk_bf16_f32 v114, v58, v59
	v_cvt_pk_bf16_f32 v115, v60, v61
	ds_read_b64_tr_b16 v[50:51], v96 offset:31744
	ds_read_b64_tr_b16 v[52:53], v96 offset:32256
	v_mfma_f32_32x32x16_bf16 v[66:81], v[158:161], v[130:133], v[66:81]
	v_add_f32_e32 v58, v64, v90
	v_add_f32_e32 v58, v65, v58
	v_cvt_pk_bf16_f32 v116, v62, v63
	v_cvt_pk_bf16_f32 v117, v64, v65
	s_add_i32 s15, s14, 0x140
	v_add_f32_e32 v184, v184, v58
	v_mad_u64_u32 v[58:59], s[62:63], s15, v233, v[214:215]
	s_add_i32 s15, s57, s78
	s_mov_b32 m0, s15
	s_nop 0
	global_load_lds_dwordx4 v[58:59], off
	v_lshl_add_u64 v[58:59], v[228:229], 0, s[54:55]
	s_lshl_b32 s15, s67, 1
	s_add_i32 s57, s15, s79
	s_mov_b32 m0, s57
	s_nop 0
	global_load_lds_dwordx4 v[58:59], off
	v_max_f32_e32 v58, v98, v99
	v_max3_f32 v59, v100, v101, v67
	v_max3_f32 v58, v58, v66, v68
	v_max3_f32 v58, v58, v69, v102
	v_max3_f32 v59, v59, v104, v105
	v_max3_f32 v58, v58, v103, v70
	v_max3_f32 v59, v59, v72, v73
	v_max3_f32 v58, v58, v71, v106
	v_max3_f32 v59, v59, v108, v109
	v_max3_f32 v58, v58, v107, v74
	v_max3_f32 v59, v59, v76, v77
	v_max3_f32 v58, v58, v75, v110
	v_max3_f32 v59, v59, v112, v113
	v_max3_f32 v58, v58, v111, v78
	v_max3_f32 v59, v59, v80, v81
	v_max3_f32 v58, v58, v79, v59
	v_mov_b32_e32 v59, v58
	s_nop 1
	v_permlane32_swap_b32_e32 v58, v59
	v_max_f32_e32 v58, v58, v59
	v_cmp_lt_f32_e32 vcc, s43, v58
	s_cmp_lg_u64 vcc, 0
	s_cselect_b64 s[62:63], -1, 0
	s_cbranch_vccnz .LBB0_431

.LBB0_334:
	s_add_i32 s13, s67, 0x2000
	s_cmpk_lg_i32 s67, 0x4000
	s_cselect_b32 s86, s13, 0
	s_add_i32 s13, s14, 0x180
	v_add_f32_e32 v199, v184, v74
	v_mad_u64_u32 v[74:75], s[70:71], s13, v233, v[214:215]
	s_add_i32 s13, s67, s78
	s_mov_b32 m0, s13
	s_nop 0
	global_load_lds_dwordx4 v[74:75], off
	s_mul_i32 s66, s80, 0x48000
	s_mov_b32 s67, s7
	v_lshl_add_u64 v[74:75], v[182:183], 0, s[66:67]
	v_lshl_add_u64 v[230:231], v[74:75], 0, s[10:11]
	v_max_f32_e32 v74, v82, v83
	v_max3_f32 v75, v84, v85, v51
	v_max3_f32 v74, v74, v50, v52
	v_max3_f32 v74, v74, v53, v86
	v_max3_f32 v75, v75, v88, v89
	v_max3_f32 v74, v74, v87, v54
	v_max3_f32 v75, v75, v56, v57
	v_max3_f32 v74, v74, v55, v90
	v_max3_f32 v75, v75, v92, v93
	v_max3_f32 v74, v74, v91, v58
	v_max3_f32 v75, v75, v60, v61
	v_max3_f32 v74, v74, v59, v94
	v_max3_f32 v75, v75, v96, v97
	v_max3_f32 v74, v74, v95, v62
	v_max3_f32 v75, v75, v64, v65
	v_max3_f32 v74, v74, v63, v75
	v_mov_b32_e32 v75, v74
	s_nop 1
	v_permlane32_swap_b32_e32 v74, v75
	s_lshl_b32 s13, s86, 1
	v_max_f32_e32 v74, v74, v75
	s_add_i32 s13, s13, s79
	s_mov_b32 m0, s13
	s_nop 0
	global_load_lds_dwordx4 v[230:231], off
	v_cmp_lt_f32_e32 vcc, s43, v74
	s_cmp_lg_u64 vcc, 0
	s_cselect_b64 s[66:67], -1, 0
	s_cbranch_vccnz .LBB0_434

.LBB0_344:
	s_add_i32 s15, s86, 0x2000
	s_cmpk_lg_i32 s86, 0x4000
	s_cselect_b32 s15, s15, 0
	s_add_i32 s64, s14, 0x1c0
	v_mad_u64_u32 v[98:99], s[64:65], s64, v233, v[214:215]
	s_add_i32 s64, s86, s78
	s_mov_b32 m0, s64
	s_nop 0
	global_load_lds_dwordx4 v[98:99], off
	s_mul_i32 s64, s57, 0x48000
	s_mov_b32 s65, s7
	v_lshl_add_u64 v[98:99], v[228:229], 0, s[64:65]
	s_lshl_b32 s57, s15, 1
	s_add_i32 s57, s57, s79
	s_mov_b32 m0, s57
	s_nop 0
	global_load_lds_dwordx4 v[98:99], off
	v_max_f32_e32 v98, v66, v67
	v_max3_f32 v99, v68, v69, v51
	v_max3_f32 v98, v98, v50, v52
	v_max3_f32 v98, v98, v53, v70
	v_max3_f32 v99, v99, v72, v73
	v_max3_f32 v98, v98, v71, v54
	v_max3_f32 v99, v99, v56, v57
	v_max3_f32 v98, v98, v55, v74
	v_max3_f32 v99, v99, v76, v77
	v_max3_f32 v98, v98, v75, v58
	v_max3_f32 v99, v99, v60, v61
	v_max3_f32 v98, v98, v59, v78
	v_max3_f32 v99, v99, v80, v81
	v_max3_f32 v98, v98, v79, v62
	v_max3_f32 v99, v99, v64, v65
	v_max3_f32 v98, v98, v63, v99
	v_mov_b32_e32 v99, v98
	s_nop 1
	v_permlane32_swap_b32_e32 v98, v99
	v_max_f32_e32 v98, v98, v99
	v_cmp_lt_f32_e32 vcc, s43, v98
	s_cmp_lg_u64 vcc, 0
	v_add_f32_e32 v220, v199, v182
	s_cselect_b64 s[64:65], -1, 0
	s_cbranch_vccnz .LBB0_437

.LBB0_355:
	v_lshl_add_u64 v[216:217], v[210:211], 0, s[64:65]
	s_mov_b64 s[70:71], 0x120000
	v_lshl_add_u64 v[82:83], v[216:217], 0, s[70:71]
	v_lshl_add_u64 v[218:219], v[212:213], 0, s[64:65]
	s_add_i32 s70, s15, s78
	s_mov_b32 m0, s70
	s_nop 0
	global_load_lds_dwordx4 v[82:83], off
	v_lshl_add_u64 v[82:83], v[218:219], 0, s[52:53]
	s_lshl_b32 s86, s84, 1
	s_add_i32 s70, s86, s79
	s_mov_b32 m0, s70
	s_nop 0
	global_load_lds_dwordx4 v[82:83], off
	v_max_f32_e32 v82, v66, v67
	v_max3_f32 v83, v68, v69, v51
	v_max3_f32 v82, v82, v50, v52
	v_max3_f32 v82, v82, v53, v70
	v_max3_f32 v83, v83, v72, v73
	v_max3_f32 v82, v82, v71, v54
	v_max3_f32 v83, v83, v56, v57
	v_max3_f32 v82, v82, v55, v74
	v_max3_f32 v83, v83, v76, v77
	v_max3_f32 v82, v82, v75, v58
	v_max3_f32 v83, v83, v60, v61
	v_max3_f32 v82, v82, v59, v78
	v_max3_f32 v83, v83, v80, v81
	v_max3_f32 v82, v82, v79, v62
	v_max3_f32 v83, v83, v64, v65
	v_max3_f32 v82, v82, v63, v83
	v_mov_b32_e32 v83, v82
	s_nop 1
	v_permlane32_swap_b32_e32 v82, v83
	v_max_f32_e32 v82, v82, v83
	v_cmp_lt_f32_e32 vcc, s43, v82
	s_cmp_lg_u64 vcc, 0
	v_add_f32_e32 v209, v220, v178
	s_cselect_b64 s[70:71], -1, 0
	s_cbranch_vccnz .LBB0_370

.LBB0_365:
	s_add_i32 s15, s84, 0x2000
	s_cmpk_lg_i32 s84, 0x4000
	s_mov_b64 s[66:67], 0x168000
	s_cselect_b32 s15, s15, 0
	v_lshl_add_u64 v[82:83], v[216:217], 0, s[66:67]
	s_add_i32 s66, s84, s78
	s_mov_b32 m0, s66
	s_nop 0
	global_load_lds_dwordx4 v[82:83], off
	v_lshl_add_u64 v[82:83], v[218:219], 0, s[54:55]
	s_lshl_b32 s72, s15, 1
	s_add_i32 s66, s72, s79
	s_mov_b32 m0, s66
	s_nop 0
	global_load_lds_dwordx4 v[82:83], off
	v_max_f32_e32 v82, v66, v67
	v_max3_f32 v83, v68, v69, v51
	v_max3_f32 v82, v82, v50, v52
	v_max3_f32 v82, v82, v53, v70
	v_max3_f32 v83, v83, v72, v73
	v_max3_f32 v82, v82, v71, v54
	v_max3_f32 v83, v83, v56, v57
	v_max3_f32 v82, v82, v55, v74
	v_max3_f32 v83, v83, v76, v77
	v_max3_f32 v82, v82, v75, v58
	v_max3_f32 v83, v83, v60, v61
	v_max3_f32 v82, v82, v59, v78
	v_max3_f32 v83, v83, v80, v81
	v_max3_f32 v82, v82, v79, v62
	v_max3_f32 v83, v83, v64, v65
	v_max3_f32 v82, v82, v63, v83
	v_mov_b32_e32 v83, v82
	s_nop 1
	v_permlane32_swap_b32_e32 v82, v83
	v_max_f32_e32 v82, v82, v83
	v_cmp_lt_f32_e32 vcc, s43, v82
	s_cmp_lg_u64 vcc, 0
	v_add_f32_e32 v220, v209, v182
	s_cselect_b64 s[66:67], -1, 0
	s_cbranch_vccnz .LBB0_373

.LBB0_383:
	s_mul_i32 s66, s66, 0x48000
	s_mov_b32 s67, s7
	v_lshl_add_u64 v[82:83], v[226:227], 0, s[66:67]
	s_mov_b64 s[70:71], 0xd8400
	v_lshl_add_u64 v[82:83], v[82:83], 0, s[70:71]
	s_add_i32 s3, s15, s78
	s_ashr_i32 s67, s66, 31
	s_mov_b32 m0, s3
	s_nop 0
	global_load_lds_dwordx4 v[82:83], off
	v_lshl_add_u64 v[82:83], v[206:207], 0, s[66:67]
	s_lshl_b32 s3, s73, 1
	s_add_i32 s15, s3, s79
	s_mov_b32 m0, s15
	s_nop 0
	global_load_lds_dwordx4 v[82:83], off
	v_max_f32_e32 v82, v66, v67
	v_max3_f32 v83, v68, v69, v51
	v_max3_f32 v82, v82, v50, v52
	v_max3_f32 v82, v82, v53, v70
	v_max3_f32 v83, v83, v72, v73
	v_max3_f32 v82, v82, v71, v54
	v_max3_f32 v83, v83, v56, v57
	v_max3_f32 v82, v82, v55, v74
	v_max3_f32 v83, v83, v76, v77
	v_max3_f32 v82, v82, v75, v58
	v_max3_f32 v83, v83, v60, v61
	v_max3_f32 v82, v82, v59, v78
	v_max3_f32 v83, v83, v80, v81
	v_max3_f32 v82, v82, v79, v62
	v_max3_f32 v83, v83, v64, v65
	v_max3_f32 v82, v82, v63, v83
	v_mov_b32_e32 v83, v82
	s_nop 1
	v_permlane32_swap_b32_e32 v82, v83
	v_max_f32_e32 v82, v82, v83
	v_cmp_lt_f32_e32 vcc, s43, v82
	s_cmp_lg_u64 vcc, 0
	v_add_f32_e32 v216, v220, v170
	s_cselect_b64 s[66:67], -1, 0
	s_cbranch_vccnz .LBB0_440

.LBB0_393:
	s_add_i32 s15, s73, 0x2000
	s_cmpk_lg_i32 s73, 0x4000
	s_cselect_b32 s15, s15, 0
	s_addk_i32 s14, 0x3c0
	v_mad_u64_u32 v[82:83], s[70:71], s14, v233, v[214:215]
	s_add_i32 s14, s73, s78
	s_mov_b32 m0, s14
	s_nop 0
	global_load_lds_dwordx4 v[82:83], off
	s_mul_i32 s66, s66, 0x48000
	s_mov_b32 s67, s7
	v_lshl_add_u64 v[82:83], v[228:229], 0, s[66:67]
	s_lshl_b32 s14, s15, 1
	s_add_i32 s66, s14, s79
	s_mov_b32 m0, s66
	s_nop 0
	global_load_lds_dwordx4 v[82:83], off
	v_max_f32_e32 v82, v66, v67
	v_max3_f32 v83, v68, v69, v51
	v_max3_f32 v82, v82, v50, v52
	v_max3_f32 v82, v82, v53, v70
	v_max3_f32 v83, v83, v72, v73
	v_max3_f32 v82, v82, v71, v54
	v_max3_f32 v83, v83, v56, v57
	v_max3_f32 v82, v82, v55, v74
	v_max3_f32 v83, v83, v76, v77
	v_max3_f32 v82, v82, v75, v58
	v_max3_f32 v83, v83, v60, v61
	v_max3_f32 v82, v82, v59, v78
	v_max3_f32 v83, v83, v80, v81
	v_max3_f32 v82, v82, v79, v62
	v_max3_f32 v83, v83, v64, v65
	v_max3_f32 v82, v82, v63, v83
	v_mov_b32_e32 v83, v82
	s_nop 1
	v_permlane32_swap_b32_e32 v82, v83
	v_max_f32_e32 v82, v82, v83
	v_cmp_lt_f32_e32 vcc, s43, v82
	s_cmp_lg_u64 vcc, 0
	v_add_f32_e32 v246, v216, v198
	s_cselect_b64 s[66:67], -1, 0
	s_cbranch_vccnz .LBB0_443

.LBB0_403:
	s_add_i32 s3, s15, 0x2000
	s_cmpk_lg_i32 s15, 0x4000
	s_cselect_b32 s3, s3, 0
	s_mul_i32 s66, s66, 0x48000
	s_mov_b32 s67, s7
	v_lshl_add_u64 v[82:83], v[228:229], 0, s[66:67]
	s_lshl_b32 s15, s3, 1
	s_add_i32 s12, s15, s79
	s_mov_b32 m0, s12
	s_nop 0
	global_load_lds_dwordx4 v[82:83], off
	v_max_f32_e32 v82, v66, v67
	v_max3_f32 v83, v68, v69, v51
	v_max3_f32 v82, v82, v50, v52
	v_max3_f32 v82, v82, v53, v70
	v_max3_f32 v83, v83, v72, v73
	v_max3_f32 v82, v82, v71, v54
	v_max3_f32 v83, v83, v56, v57
	v_max3_f32 v82, v82, v55, v74
	v_max3_f32 v83, v83, v76, v77
	v_max3_f32 v82, v82, v75, v58
	v_max3_f32 v83, v83, v60, v61
	v_max3_f32 v82, v82, v59, v78
	v_max3_f32 v83, v83, v80, v81
	v_max3_f32 v82, v82, v79, v62
	v_max3_f32 v83, v83, v64, v65
	v_max3_f32 v82, v82, v63, v83
	v_mov_b32_e32 v83, v82
	s_nop 1
	v_permlane32_swap_b32_e32 v82, v83
	v_max_f32_e32 v82, v82, v83
	v_cmp_lt_f32_e32 vcc, s43, v82
	s_cmp_lg_u64 vcc, 0
	v_add_f32_e32 v246, v246, v198
	s_cselect_b64 s[66:67], -1, 0
	s_cbranch_vccnz .LBB0_446

.LBB0_413:
	s_add_i32 s12, s3, 0x2000
	s_cmpk_lg_i32 s3, 0x4000
	s_cselect_b32 s13, s12, 0
	s_mov_b64 s[62:63], 0x318000
	v_lshl_add_u64 v[82:83], v[230:231], 0, s[62:63]
	s_lshl_b32 s12, s13, 1
	s_add_i32 s14, s12, s79
	s_mov_b32 m0, s14
	s_nop 0
	global_load_lds_dwordx4 v[82:83], off
	v_max_f32_e32 v82, v66, v67
	v_max3_f32 v83, v68, v69, v51
	v_max3_f32 v82, v82, v50, v52
	v_max3_f32 v82, v82, v53, v70
	v_max3_f32 v83, v83, v72, v73
	v_max3_f32 v82, v82, v71, v54
	v_max3_f32 v83, v83, v56, v57
	v_max3_f32 v82, v82, v55, v74
	v_max3_f32 v83, v83, v76, v77
	v_max3_f32 v82, v82, v75, v58
	v_max3_f32 v83, v83, v60, v61
	v_max3_f32 v82, v82, v59, v78
	v_max3_f32 v83, v83, v80, v81
	v_max3_f32 v82, v82, v79, v62
	v_max3_f32 v83, v83, v64, v65
	v_max3_f32 v82, v82, v63, v83
	v_mov_b32_e32 v83, v82
	s_nop 1
	v_permlane32_swap_b32_e32 v82, v83
	v_max_f32_e32 v82, v82, v83
	v_cmp_lt_f32_e32 vcc, s43, v82
	s_cmp_lg_u64 vcc, 0
	v_add_f32_e32 v194, v246, v198
	s_cselect_b64 s[62:63], -1, 0
	s_cbranch_vccnz .LBB0_449

; template <int l> __device__ __forceinline__ void layer_body(const Args& a, unsigned char* lds, const XcdBarrier& bar, int G, int bx, int vcu, int gw, int NGW, int lane_, int tid_k, int wave) {
;     ...
;                     const int n2 = n + 1; const bool hasn = (i + 1 < pern) && (n2 < 1024); const int b2 = n2 >> 8, h2 = (n2 >> 5) & 7; const size_t rb2 = (size_t)b2 * TPB;
;                     attn_body::attn_unit<1, 8>(qkv + rq * PAR_IN + h * 64, PAR_IN, qkv + rb * PAR_IN + 512 + h * 64, PAR_IN, qkv + rb * PAR_IN + 1024 + h * 64, PAR_IN,
;                                                (abf*)AO + rq * DMODEL + h * 64, DMODEL, 16, nb, r0, (const float*)(ws + WS_MF) + (size_t)h * (15 * 2 * 64 * 16), (char*)lds,
;                                                rot, pre, hasn, (long)((rb2 * PAR_IN + h2 * 64) - (rb * PAR_IN + h * 64)), (long)((rb2 * PAR_IN + h2 * 64) - (rb * PAR_IN + h * 64)));
.LBB0_421:
	s_add_i32 s14, s13, 0x2000
	s_cmpk_lg_i32 s13, 0x4000
	s_cselect_b32 s14, s14, 0
	s_add_i32 s75, s75, 1
	s_cmp_lt_i32 s75, s0
	s_cselect_b64 s[62:63], -1, 0
	s_cmpk_lg_i32 s77, 0x3ff
	s_cselect_b64 s[64:65], -1, 0
	s_and_b64 s[62:63], s[62:63], s[64:65]
	s_andn2_b64 vcc, exec, s[62:63]
	s_cbranch_vccnz .LBB0_423
	s_add_i32 s77, s77, 1
	s_ashr_i32 s15, s77, 8
	s_lshl_b32 s65, s77, 1
	s_mul_hi_i32 s64, s15, 0x1290000
	s_mul_i32 s15, s15, 0x1290000
	s_and_b32 s65, s65, 0x1c0
	s_or_b32 s15, s15, s65
	s_or_b64 s[60:61], s[60:61], s[6:7]
	s_sub_u32 s60, s15, s60
	s_subb_u32 s61, s64, s61
	s_lshl_b64 s[60:61], s[60:61], 1
	v_lshl_add_u64 v[68:69], v[226:227], 0, s[60:61]
	s_add_i32 s6, s14, s78
	v_lshl_add_u64 v[70:71], v[68:69], 0, s[8:9]
	s_mov_b32 m0, s6
	s_nop 0
	global_load_lds_dwordx4 v[70:71], off
	s_lshl_b32 s6, s14, 1
	v_lshl_add_u64 v[72:73], v[228:229], 0, s[60:61]
	s_add_i32 s6, s6, s79
	s_mov_b32 m0, s6
	s_nop 0
	global_load_lds_dwordx4 v[72:73], off
	s_mov_b64 s[60:61], 0x48400
	v_lshl_add_u64 v[70:71], v[68:69], 0, s[60:61]
	s_add_i32 s3, s3, s78
	s_mov_b32 m0, s3
	s_nop 0
	global_load_lds_dwordx4 v[70:71], off
	s_mov_b64 s[60:61], 0x90400
	v_lshl_add_u64 v[68:69], v[68:69], 0, s[60:61]
	s_add_i32 s3, s13, s78
	s_mov_b32 m0, s3
	s_nop 0
	global_load_lds_dwordx4 v[68:69], off

;   #define DMA_K(t,slot) glds16(ksrc+(long)KROW(t)*PK,(unsigned)__builtin_amdgcn_readfirstlane(kdst+(slot)))
;   #define DMA_V(t,slot) do{ glds16(vsrc+(long)KROW(t)*PV,(unsigned)__builtin_amdgcn_readfirstlane(vdst+2*(slot))); if(MODE==2)glds16(vsrc+(long)KROW(t)*PV+64,(unsigned)__builtin_amdgcn_readfirstlane(vdst+2*(slot)+SLOTB)); }while(0)
; template<int MODE,int THRL> __device__ __forceinline__ void attn_unit(const bf16*Qw0,int PQ,const bf16*__restrict__ Kh,int PK,const bf16*__restrict__ Vh,int PV,bf16*Ow0,int PO,int NT,int nabase,int nar0,const float*rpbh,char*shm,int&rot,bool pre,bool hasn,long dKn,long dVn){
;     ...
;   int tid_=threadIdx.x; asm volatile("":"+v"(tid_));
;   const int tid=tid_,lane=tid&63,r32=lane&31,hi=lane>>5; const int wid=__builtin_amdgcn_readfirstlane(tid>>6);
;   const bf16*Qw=Qw0+(long)wid*QBLK*PQ;
;   const unsigned lds0=(unsigned)(uintptr_t)shm;
;   float*wsf=(float*)(shm+LDS_WS)+wid*64;
;   const bf16*ksrc=Kh+(long)lane*PK+wid*8;
;   const bf16*vsrc=Vh+(long)(16*(wid&3)+(lane>>2))*PV+(wid>>2)*32+(lane&3)*8;
;   const unsigned kdst=lds0+LDS_K+wid*1024, vdst=lds0+LDS_V+wid*1024;
;     ...
;   const int vb0=(int)(lds0+LDS_V)+((lane>>4)&1)*32+(lane&3)*8+(4*hi+((lane&15)>>2))*64;
;   const char*Kbase=shm+LDS_K; bf16x8 kf[8];
;   const lds_cptr shm3=(lds_cptr)shm; const lds_cptr kp0=shm3+LDS_K+hi*1024+r32*16; const lds_cptr vp0=shm3+LDS_V+((lane>>4)&1)*32+(lane&3)*8+(4*hi+((lane&15)>>2))*64;
;   const lds_cfptr tb=(lds_cfptr)(shm3+LDS_TB);
;   u32x4_t mf[4];
;   const int nar=nar0+(wid>>1), nac=(wid&1)*32+r32;
;   if(!pre){ DMA_K(0,rot);DMA_V(0,rot);DMA_K(1,NXT(rot)); }
.LBB0_478:
	v_mov_b32_e32 v34, v222
	s_xor_b64 s[10:11], s[10:11], -1
	v_and_b32_e32 v211, 63, v34
	v_readfirstlane_b32 s3, v34
	v_mul_u32_u24_e32 v0, 0x900, v211
	s_ashr_i32 s66, s3, 6
	v_lshlrev_b32_e32 v0, 1, v0
	v_lshl_add_u64 v[2:3], s[70:71], 0, v[0:1]
	s_lshl_b32 s15, s66, 4
	v_bfe_u32 v0, v34, 2, 4
	s_lshl_b32 s80, s66, 3
	v_and_or_b32 v0, s15, 48, v0
	s_ashr_i32 s81, s80, 31
	v_mul_u32_u24_e32 v0, 0x900, v0
	s_ashr_i32 s15, s3, 3
	v_lshl_add_u64 v[204:205], s[80:81], 1, v[2:3]
	v_lshlrev_b32_e32 v0, 1, v0
	s_and_b32 s80, s15, 0xffffffe0
	v_lshlrev_b32_e32 v212, 3, v34
	v_lshl_add_u64 v[2:3], s[72:73], 0, v[0:1]
	s_ashr_i32 s81, s80, 31
	v_and_b32_e32 v215, 24, v212
	v_lshl_add_u64 v[2:3], s[80:81], 1, v[2:3]
	v_lshlrev_b32_e32 v0, 1, v215
	s_lshl_b32 s15, s66, 10
	v_lshl_add_u64 v[206:207], v[2:3], 0, v[0:1]
	s_add_i32 s33, s15, 0x6000
	s_mov_b64 s[80:81], -1
	s_and_b64 vcc, exec, s[10:11]
	s_cbranch_vccz .LBB0_480
	s_add_i32 s43, s15, s82
	s_mov_b32 m0, s43
	s_nop 0
	global_load_lds_dwordx4 v[204:205], off
	s_lshl_b32 s43, s82, 1
	s_add_i32 s43, s33, s43
	s_mov_b32 m0, s43
	s_nop 0
	global_load_lds_dwordx4 v[206:207], off
	s_add_i32 s43, s82, 0x2000
	s_cmpk_lg_i32 s82, 0x4000
	s_cselect_b32 s52, s43, 0
	v_lshl_add_u64 v[2:3], v[204:205], 0, s[54:55]
	s_add_i32 s52, s15, s52
	s_mov_b32 m0, s52
	s_nop 0
	global_load_lds_dwordx4 v[2:3], off
	s_mov_b64 s[80:81], 0

; #define WAIT_BAR(N) asm volatile("s_waitcnt vmcnt(" #N ") lgkmcnt(0)\n\ts_barrier":::"memory")
;   #define DMA_K(t,slot) glds16(ksrc+(long)KROW(t)*PK,(unsigned)__builtin_amdgcn_readfirstlane(kdst+(slot)))
; template<int MODE,int THRL> __device__ __forceinline__ void attn_unit(const bf16*Qw0,int PQ,const bf16*__restrict__ Kh,int PK,const bf16*__restrict__ Vh,int PV,bf16*Ow0,int PO,int NT,int nabase,int nar0,const float*rpbh,char*shm,int&rot,bool pre,bool hasn,long dKn,long dVn){
;     ...
;   bf16x8 qr[4];
;   #pragma unroll
;   for(int d0=0;d0<4;++d0)qr[d0]=*reinterpret_cast<const bf16x8*>(&Qw[(long)r32*PQ+d0*16+hi*8]);
;   float mhat=0.f,l_reg=0.f;constexpr int ND=(MODE==2)?4:2; f32x16 o[4];o[0]=f32x16{};o[1]=f32x16{};o[2]=f32x16{};o[3]=f32x16{};f32x16 negm=f32x16{};asm volatile("":"+v"(negm));
;     ...
;   bool resc=false;
;     ...
;   f32x16 pA0,pA1,pB0,pB1;
;   int sl_prev=rot,sl_cur=rot,sl_next=NXT(rot);
;   bool pfnow=false;
;     ...
;   if(!pre){ DMA_K(2,NXT(sl_next)); }
;   if(pre){WAIT_BAR(0);}else if(MODE==2){WAIT_BAR(4);}else{WAIT_BAR(3);}
.LBB0_482:
	v_and_b32_e32 v213, 31, v34
	s_mul_i32 s67, s66, 0x24000
	v_mul_u32_u24_e32 v0, 0x900, v213
	v_lshrrev_b32_e32 v214, 5, v211
	s_mul_hi_i32 s52, s66, 0x24000
	s_add_u32 s78, s78, s67
	v_lshlrev_b32_e32 v0, 1, v0
	s_addc_u32 s79, s79, s52
	v_lshl_or_b32 v0, v214, 4, v0
	global_load_dwordx4 v[148:151], v0, s[78:79]
	global_load_dwordx4 v[140:143], v0, s[78:79] offset:32
	global_load_dwordx4 v[132:135], v0, s[78:79] offset:64
	global_load_dwordx4 v[128:131], v0, s[78:79] offset:96
	v_mov_b32_e32 v2, v1
	v_mov_b32_e32 v3, v1
	v_mov_b32_e32 v4, v1
	v_mov_b32_e32 v5, v1
	v_mov_b32_e32 v6, v1
	v_mov_b32_e32 v7, v1
	v_mov_b32_e32 v8, v1
	v_mov_b32_e32 v9, v1
	v_mov_b32_e32 v10, v1
	v_mov_b32_e32 v11, v1
	v_mov_b32_e32 v12, v1
	v_mov_b32_e32 v13, v1
	v_mov_b32_e32 v14, v1
	v_mov_b32_e32 v15, v1
	v_mov_b32_e32 v0, v1
	v_mov_b64_e32 v[16:17], v[14:15]
	s_cmpk_lg_i32 s82, 0x4000
	v_mov_b64_e32 v[14:15], v[12:13]
	v_mov_b64_e32 v[12:13], v[10:11]
	v_mov_b64_e32 v[10:11], v[8:9]
	v_mov_b64_e32 v[8:9], v[6:7]
	v_mov_b64_e32 v[6:7], v[4:5]
	v_mov_b64_e32 v[4:5], v[2:3]
	v_mov_b64_e32 v[2:3], v[0:1]
	s_cselect_b32 s43, s43, 0
	s_andn2_b64 vcc, exec, s[10:11]
	s_mov_b64 s[10:11], -1
	s_cbranch_vccnz .LBB0_484
	s_add_i32 s52, s43, 0x2000
	s_cmpk_lg_i32 s43, 0x4000
	s_cselect_b32 s10, s52, 0
	v_lshl_add_u64 v[18:19], v[204:205], 0, s[56:57]
	s_add_i32 s10, s10, s15
	s_mov_b32 m0, s10
	s_nop 0
	global_load_lds_dwordx4 v[18:19], off
	s_waitcnt vmcnt(3) lgkmcnt(0)
	s_barrier
	s_mov_b64 s[10:11], 0

; #define WAIT_BAR(N) asm volatile("s_waitcnt vmcnt(" #N ") lgkmcnt(0)\n\ts_barrier":::"memory")
;   #define DMA_K(t,slot) glds16(ksrc+(long)KROW(t)*PK,(unsigned)__builtin_amdgcn_readfirstlane(kdst+(slot)))
;   #define DMA_V(t,slot) do{ glds16(vsrc+(long)KROW(t)*PV,(unsigned)__builtin_amdgcn_readfirstlane(vdst+2*(slot))); if(MODE==2)glds16(vsrc+(long)KROW(t)*PV+64,(unsigned)__builtin_amdgcn_readfirstlane(vdst+2*(slot)+SLOTB)); }while(0)
;   #define CMASK(P0,P1,t) do{ if(MODE==1&&(t)>=4)na_apply(P0,P1,mf,na_rowok((t),nabase,nar)); }while(0)
;   #define ROT() do{sl_prev=sl_cur;sl_cur=sl_next;sl_next=(sl_next==(NSLOT-1)*SLOTB)?0:sl_next+SLOTB;}while(0)
; __device__ __forceinline__ void qkt(f32x16&p0,f32x16&p1,const char*Kslot,const bf16x8*qr,const f32x16&negm,int r32,int hi){
;   const char*kb=Kslot+hi*1024+r32*16;
;   #pragma unroll
;   for(int d0=0;d0<4;++d0){
;     const bf16x8 b0=*reinterpret_cast<const bf16x8*>(kb+d0*2048);
;     const bf16x8 b1=*reinterpret_cast<const bf16x8*>(kb+d0*2048+512);
;     if(d0==0){p0=__builtin_amdgcn_mfma_f32_32x32x16_bf16(b0,qr[0],negm,0,0,0);p1=__builtin_amdgcn_mfma_f32_32x32x16_bf16(b1,qr[0],negm,0,0,0);}
;     else{p0=__builtin_amdgcn_mfma_f32_32x32x16_bf16(b0,qr[d0],p0,0,0,0);p1=__builtin_amdgcn_mfma_f32_32x32x16_bf16(b1,qr[d0],p1,0,0,0);}}
; template<int MODE,int THRL> __device__ __forceinline__ void attn_unit(const bf16*Qw0,int PQ,const bf16*__restrict__ Kh,int PK,const bf16*__restrict__ Vh,int PV,bf16*Ow0,int PO,int NT,int nabase,int nar0,const float*rpbh,char*shm,int&rot,bool pre,bool hasn,long dKn,long dVn){
;     ...
;   f32x16 pA0,pA1,pB0,pB1;
;   int sl_prev=rot,sl_cur=rot,sl_next=NXT(rot);
;   bool pfnow=false;
;     ...
;   if(!pre){ DMA_K(2,NXT(sl_next)); }
;   if(pre){WAIT_BAR(0);}else if(MODE==2){WAIT_BAR(4);}else{WAIT_BAR(3);}
;   qkt(pA0,pA1,Kbase+sl_cur,qr,negm,r32,hi);asm volatile("s_nop 15\n\ts_nop 7":"+v"(pA0),"+v"(pA1));CMASK(pA0,pA1,0);
;   START(pA0,pA1);
;   _Pragma("unroll") for(int r=0;r<16;++r)pA1[r]=__builtin_amdgcn_exp2f(pA1[r]);
;   WAIT_BAR(0);
;   DMA_K(3,sl_cur);DMA_V(1,sl_next);
;   ROT();
;   kload8(kf,kp0+sl_cur);
;   if(MODE==2){WAIT_BAR(3);}else{WAIT_BAR(2);}
.LBB0_486:
	v_lshlrev_b32_e32 v0, 10, v214
	v_lshlrev_b32_e32 v35, 4, v213
	v_add3_u32 v44, s82, v0, v35
	ds_read_b128 v[36:39], v44
	ds_read_b128 v[40:43], v44 offset:512
	v_or_b32_e32 v221, v0, v35
	s_add_i32 s10, s15, s82
	s_waitcnt vmcnt(3) lgkmcnt(1)
	v_mfma_f32_32x32x16_bf16 v[18:33], v[36:39], v[148:151], v[2:17]
	v_lshl_add_u64 v[196:197], v[206:207], 0, s[54:55]
	s_and_b32 s3, s3, 0x3fffffc0
	s_lshl_b32 s3, s3, 2
	s_add_i32 s3, s3, 0x12000
	s_mov_b32 s86, 1
	v_lshlrev_b32_e32 v224, 4, v214
	v_lshl_add_u32 v218, v213, 2, s3
	s_waitcnt lgkmcnt(0)
	v_mfma_f32_32x32x16_bf16 v[2:17], v[40:43], v[148:151], v[2:17]
	ds_read_b128 v[36:39], v44 offset:2048
	ds_read_b128 v[40:43], v44 offset:2560
	s_waitcnt vmcnt(2) lgkmcnt(1)
	v_mfma_f32_32x32x16_bf16 v[18:33], v[36:39], v[140:143], v[18:33]
	s_waitcnt lgkmcnt(0)
	v_mfma_f32_32x32x16_bf16 v[2:17], v[40:43], v[140:143], v[2:17]
	ds_read_b128 v[36:39], v44 offset:4096
	ds_read_b128 v[40:43], v44 offset:4608
	s_waitcnt vmcnt(1) lgkmcnt(1)
	v_mfma_f32_32x32x16_bf16 v[18:33], v[36:39], v[132:135], v[18:33]
	s_waitcnt lgkmcnt(0)
	v_mfma_f32_32x32x16_bf16 v[2:17], v[40:43], v[132:135], v[2:17]
	ds_read_b128 v[36:39], v44 offset:6144
	ds_read_b128 v[40:43], v44 offset:6656
	s_waitcnt vmcnt(0) lgkmcnt(1)
	v_mfma_f32_32x32x16_bf16 v[18:33], v[36:39], v[128:131], v[18:33]
	v_lshlrev_b32_e32 v36, 1, v34
	v_lshlrev_b32_e32 v34, 4, v34
	v_and_b32_e32 v34, 0xc0, v34
	v_lshl_or_b32 v217, v214, 8, v34
	v_and_b32_e32 v216, 32, v36
	v_or3_b32 v220, v216, v215, v217
	s_waitcnt lgkmcnt(0)
	v_mfma_f32_32x32x16_bf16 v[2:17], v[40:43], v[128:131], v[2:17]
	s_nop 15
	s_nop 7
	s_nop 0
	v_max3_f32 v0, v18, v19, v2
	v_max3_f32 v34, v20, v21, v3
	s_nop 0
	v_max3_f32 v0, v0, v4, v5
	v_max3_f32 v34, v34, v24, v25
	s_nop 0
	v_max3_f32 v0, v0, v22, v23
	v_max3_f32 v34, v34, v8, v9
	s_nop 0
	v_max3_f32 v0, v0, v6, v7
	v_max3_f32 v34, v34, v28, v29
	s_nop 0
	v_max3_f32 v0, v0, v26, v27
	v_max3_f32 v34, v34, v12, v13
	s_nop 0
	v_max3_f32 v0, v0, v10, v11
	v_max3_f32 v34, v34, v32, v33
	s_nop 0
	v_max3_f32 v0, v0, v30, v31
	v_max3_f32 v34, v34, v16, v17
	s_nop 0
	v_max3_f32 v0, v0, v14, v15
	s_nop 0
	v_max_f32_e32 v0, v0, v34
	s_nop 0
	v_mov_b32_e32 v34, v0
	s_nop 1
	v_permlane32_swap_b32_e32 v0, v34
	v_max_f32_e32 v0, v0, v34
	s_nop 0
	v_max_f32_e32 v0, s100, v0
	v_add_f32_e32 v219, v1, v0
	v_sub_f32_e32 v2, v2, v0
	v_sub_f32_e32 v3, v3, v0
	v_sub_f32_e32 v18, v18, v0
	v_sub_f32_e32 v19, v19, v0
	v_sub_f32_e32 v20, v20, v0
	s_nop 0
	v_xor_b32_e32 v48, 0x80000000, v219
	v_mov_b32_e32 v49, v48
	v_mov_b32_e32 v50, v48
	v_mov_b32_e32 v51, v48
	v_mov_b32_e32 v52, v48
	v_mov_b32_e32 v53, v48
	v_mov_b32_e32 v54, v48
	v_mov_b32_e32 v55, v48
	v_mov_b32_e32 v56, v48
	v_mov_b32_e32 v57, v48
	v_mov_b32_e32 v58, v48
	v_mov_b32_e32 v59, v48
	v_mov_b32_e32 v60, v48
	v_mov_b32_e32 v61, v48
	v_mov_b32_e32 v62, v48
	v_mov_b32_e32 v63, v48
	s_waitcnt vmcnt(0) lgkmcnt(0)
	s_barrier
	v_sub_f32_e32 v4, v4, v0
	v_sub_f32_e32 v21, v21, v0
	v_sub_f32_e32 v5, v5, v0
	v_sub_f32_e32 v22, v22, v0
	v_sub_f32_e32 v6, v6, v0
	v_sub_f32_e32 v23, v23, v0
	v_sub_f32_e32 v7, v7, v0
	v_sub_f32_e32 v24, v24, v0
	v_sub_f32_e32 v8, v8, v0
	v_sub_f32_e32 v25, v25, v0
	v_sub_f32_e32 v9, v9, v0
	v_sub_f32_e32 v26, v26, v0
	v_sub_f32_e32 v10, v10, v0
	v_sub_f32_e32 v27, v27, v0
	v_sub_f32_e32 v11, v11, v0
	v_sub_f32_e32 v28, v28, v0
	v_sub_f32_e32 v12, v12, v0
	v_sub_f32_e32 v29, v29, v0
	v_sub_f32_e32 v13, v13, v0
	v_sub_f32_e32 v30, v30, v0
	v_sub_f32_e32 v14, v14, v0
	v_sub_f32_e32 v31, v31, v0
	v_sub_f32_e32 v15, v15, v0
	v_sub_f32_e32 v32, v32, v0
	v_sub_f32_e32 v16, v16, v0
	v_sub_f32_e32 v33, v33, v0
	v_sub_f32_e32 v0, v17, v0
	v_exp_f32_e32 v64, v2
	v_exp_f32_e32 v65, v3
	v_lshl_add_u64 v[2:3], v[204:205], 0, s[58:59]
	s_mov_b32 m0, s10
	s_nop 0
	global_load_lds_dwordx4 v[2:3], off
	s_lshl_b32 s10, s43, 1
	v_exp_f32_e32 v79, v0
	s_add_i32 s10, s10, s33
	s_mov_b32 m0, s10
	s_nop 0
	global_load_lds_dwordx4 v[196:197], off
	v_add_u32_e32 v0, s43, v221
	ds_read_b128 v[188:191], v0
	ds_read_b128 v[184:187], v0 offset:512
	ds_read_b128 v[180:183], v0 offset:2048
	ds_read_b128 v[176:179], v0 offset:2560
	ds_read_b128 v[172:175], v0 offset:4096
	ds_read_b128 v[168:171], v0 offset:4608
	ds_read_b128 v[164:167], v0 offset:6144
	ds_read_b128 v[160:163], v0 offset:6656
	v_exp_f32_e32 v80, v18
	v_exp_f32_e32 v81, v19
	v_exp_f32_e32 v82, v20
	v_exp_f32_e32 v83, v21
	v_exp_f32_e32 v84, v22
	v_exp_f32_e32 v85, v23
	v_exp_f32_e32 v86, v24
	v_exp_f32_e32 v87, v25
	v_exp_f32_e32 v88, v26
	v_exp_f32_e32 v89, v27
	v_exp_f32_e32 v90, v28
	v_exp_f32_e32 v91, v29
	v_exp_f32_e32 v92, v30
	v_exp_f32_e32 v93, v31
	v_exp_f32_e32 v94, v32
	v_exp_f32_e32 v95, v33
	v_exp_f32_e32 v66, v4
	v_exp_f32_e32 v67, v5
	v_exp_f32_e32 v68, v6
	v_exp_f32_e32 v69, v7
	v_exp_f32_e32 v70, v8
	v_exp_f32_e32 v71, v9
	v_exp_f32_e32 v72, v10
	v_exp_f32_e32 v73, v11
	v_exp_f32_e32 v74, v12
	v_exp_f32_e32 v75, v13
	v_exp_f32_e32 v76, v14
	v_exp_f32_e32 v77, v15
	v_exp_f32_e32 v78, v16
	s_waitcnt vmcnt(2) lgkmcnt(0)
	s_barrier
	s_cmpk_lg_i32 s43, 0x4000
	s_cselect_b32 s52, s52, 0
	s_andn2_b64 vcc, exec, s[8:9]
	v_cmp_gt_u32_e64 s[8:9], 32, v211
	s_cbranch_vccnz .LBB0_502
	v_mov_b32_e32 v14, v1
	v_mov_b32_e32 v15, v1
	s_mov_b64 s[10:11], 0x168000
	v_mov_b32_e32 v0, v1
	v_mov_b32_e32 v2, v1
	v_mov_b32_e32 v3, v1
	v_mov_b32_e32 v4, v1
	v_mov_b32_e32 v5, v1
	v_mov_b32_e32 v6, v1
	v_mov_b32_e32 v7, v1
	v_mov_b32_e32 v8, v1
	v_mov_b32_e32 v9, v1
	v_mov_b32_e32 v10, v1
	v_mov_b32_e32 v11, v1
	v_mov_b32_e32 v12, v1
	v_mov_b32_e32 v13, v1
	v_mov_b64_e32 v[46:47], v[14:15]
	v_mov_b64_e32 v[30:31], v[14:15]
	v_lshl_add_u64 v[198:199], v[206:207], 0, s[58:59]
	v_lshl_add_u64 v[200:201], v[204:205], 0, s[10:11]
	v_mov_b32_e32 v225, 0
	s_mov_b32 s67, 6
	v_mov_b64_e32 v[44:45], v[12:13]
	v_mov_b64_e32 v[42:43], v[10:11]
	v_mov_b64_e32 v[40:41], v[8:9]
	v_mov_b64_e32 v[38:39], v[6:7]
	v_mov_b64_e32 v[36:37], v[4:5]
	v_mov_b64_e32 v[34:35], v[2:3]
	v_mov_b64_e32 v[32:33], v[0:1]
	v_mov_b64_e32 v[28:29], v[12:13]
	v_mov_b64_e32 v[26:27], v[10:11]
	v_mov_b64_e32 v[24:25], v[8:9]
	v_mov_b64_e32 v[22:23], v[6:7]
	v_mov_b64_e32 v[20:21], v[4:5]
	v_mov_b64_e32 v[18:19], v[2:3]
	v_mov_b64_e32 v[16:17], v[0:1]
.LBB0_488:
	v_lshl_add_u32 v0, s82, 1, v220
	ds_read_b64_tr_b16 v[192:193], v0 offset:24576
	ds_read_b64_tr_b16 v[194:195], v0 offset:25088
	s_waitcnt lgkmcnt(9)
	v_mfma_f32_32x32x16_bf16 v[112:127], v[188:191], v[148:151], v[48:63]
	v_add_f32_e32 v2, v80, v81
	v_add_f32_e32 v2, v82, v2
	v_add_f32_e32 v2, v83, v2
	v_add_f32_e32 v2, v84, v2
	v_add_f32_e32 v2, v85, v2
	v_cvt_pk_bf16_f32 v156, v80, v81
	v_cvt_pk_bf16_f32 v157, v82, v83
	ds_read_b64_tr_b16 v[188:189], v0 offset:28672
	ds_read_b64_tr_b16 v[190:191], v0 offset:29184
	s_waitcnt lgkmcnt(10)
	v_mfma_f32_32x32x16_bf16 v[96:111], v[184:187], v[148:151], v[48:63]
	v_add_f32_e32 v2, v86, v2
	v_add_f32_e32 v2, v87, v2
	v_add_f32_e32 v2, v88, v2
	v_add_f32_e32 v2, v89, v2
	v_cvt_pk_bf16_f32 v158, v84, v85
	v_cvt_pk_bf16_f32 v159, v86, v87
	ds_read_b64_tr_b16 v[184:185], v0 offset:25600
	ds_read_b64_tr_b16 v[186:187], v0 offset:26112
	s_waitcnt lgkmcnt(11)
	v_mfma_f32_32x32x16_bf16 v[112:127], v[180:183], v[140:143], v[112:127]
	v_add_f32_e32 v2, v90, v2
	v_add_f32_e32 v2, v91, v2
	v_add_f32_e32 v2, v92, v2
	v_add_f32_e32 v2, v93, v2
	v_cvt_pk_bf16_f32 v152, v88, v89
	v_cvt_pk_bf16_f32 v153, v90, v91
	ds_read_b64_tr_b16 v[84:85], v0 offset:29696
	ds_read_b64_tr_b16 v[86:87], v0 offset:30208
	s_waitcnt lgkmcnt(12)
	v_mfma_f32_32x32x16_bf16 v[96:111], v[176:179], v[140:143], v[96:111]
	v_add_f32_e32 v2, v94, v2
	v_add_f32_e32 v2, v95, v2
	v_add_f32_e32 v2, v64, v2
	v_add_f32_e32 v2, v65, v2
	v_cvt_pk_bf16_f32 v154, v92, v93
	v_cvt_pk_bf16_f32 v155, v94, v95
	ds_read_b64_tr_b16 v[80:81], v0 offset:26624
	ds_read_b64_tr_b16 v[82:83], v0 offset:27136
	s_waitcnt lgkmcnt(13)
	v_mfma_f32_32x32x16_bf16 v[112:127], v[172:175], v[132:135], v[112:127]
	v_add_f32_e32 v2, v66, v2
	v_add_f32_e32 v2, v67, v2
	v_add_f32_e32 v2, v68, v2
	v_add_f32_e32 v2, v69, v2
	v_cvt_pk_bf16_f32 v144, v64, v65
	v_cvt_pk_bf16_f32 v145, v66, v67
	ds_read_b64_tr_b16 v[10:11], v0 offset:30720
	ds_read_b64_tr_b16 v[12:13], v0 offset:31232
	s_waitcnt lgkmcnt(14)
	v_mfma_f32_32x32x16_bf16 v[96:111], v[168:171], v[132:135], v[96:111]
	v_add_f32_e32 v2, v70, v2
	v_add_f32_e32 v2, v71, v2
	v_add_f32_e32 v2, v72, v2
	v_add_f32_e32 v2, v73, v2
	v_cvt_pk_bf16_f32 v146, v68, v69
	v_cvt_pk_bf16_f32 v147, v70, v71
	ds_read_b64_tr_b16 v[6:7], v0 offset:27648
	ds_read_b64_tr_b16 v[8:9], v0 offset:28160
	s_waitcnt lgkmcnt(14)
	v_mfma_f32_32x32x16_bf16 v[112:127], v[164:167], v[128:131], v[112:127]
	v_add_f32_e32 v2, v74, v2
	v_add_f32_e32 v2, v75, v2
	v_add_f32_e32 v2, v76, v2
	v_add_f32_e32 v14, v77, v2
	v_cvt_pk_bf16_f32 v136, v72, v73
	v_cvt_pk_bf16_f32 v137, v74, v75
	ds_read_b64_tr_b16 v[2:3], v0 offset:31744
	ds_read_b64_tr_b16 v[4:5], v0 offset:32256
	v_mfma_f32_32x32x16_bf16 v[96:111], v[160:163], v[128:131], v[96:111]
	v_add_f32_e32 v0, v78, v14
	v_add_f32_e32 v0, v79, v0
	v_cvt_pk_bf16_f32 v138, v76, v77
	v_cvt_pk_bf16_f32 v139, v78, v79
	v_lshl_add_u64 v[14:15], v[200:201], 0, s[60:61]
	s_add_i32 s10, s43, s15
	s_mov_b32 m0, s10
	s_nop 0
	global_load_lds_dwordx4 v[14:15], off
	v_lshl_add_u64 v[14:15], v[198:199], 0, s[60:61]
	s_lshl_b32 s10, s52, 1
	s_add_i32 s10, s10, s33
	s_mov_b32 m0, s10
	s_nop 0
	global_load_lds_dwordx4 v[14:15], off
	s_cmp_lg_u32 s98, 0
	s_cbranch_scc1 .Lbm_skip_a
	v_max_f32_e32 v14, v112, v113
	v_max3_f32 v15, v114, v115, v97
	v_max3_f32 v14, v14, v96, v98
	v_max3_f32 v14, v14, v99, v116
	v_max3_f32 v15, v15, v118, v119
	v_max3_f32 v14, v14, v117, v100
	v_max3_f32 v15, v15, v102, v103
	v_max3_f32 v14, v14, v101, v120
	v_max3_f32 v15, v15, v122, v123
	v_max3_f32 v14, v14, v121, v104
	v_max3_f32 v15, v15, v106, v107
	v_max3_f32 v14, v14, v105, v124
	v_max3_f32 v15, v15, v126, v127
	v_max3_f32 v64, v14, v125, v108
	v_max3_f32 v15, v15, v110, v111
	v_add_f32_e32 v14, v225, v0
	v_max3_f32 v0, v64, v109, v15
	v_mov_b32_e32 v15, v0
	s_nop 1
	v_permlane32_swap_b32_e32 v0, v15
	v_max_f32_e32 v0, v0, v15
	v_cmp_lt_f32_e32 vcc, s13, v0
	s_cmp_lg_u64 vcc, 0
	s_cselect_b64 s[10:11], -1, 0
	s_cbranch_vccnz .LBB0_496
	s_branch .LBB0_489

.LBB0_491:
	s_add_i32 s10, s52, 0x2000
	s_cmpk_lg_i32 s52, 0x4000
	s_cselect_b32 s80, s10, 0
	v_lshl_add_u32 v4, s43, 1, v220
	ds_read_b64_tr_b16 v[168:169], v4 offset:24576
	ds_read_b64_tr_b16 v[170:171], v4 offset:25088
	s_waitcnt lgkmcnt(9)
	v_mfma_f32_32x32x16_bf16 v[80:95], v[64:67], v[148:151], v[48:63]
	v_add_f32_e32 v2, v112, v113
	v_add_f32_e32 v2, v114, v2
	v_add_f32_e32 v2, v115, v2
	v_add_f32_e32 v2, v116, v2
	v_add_f32_e32 v2, v117, v2
	v_cvt_pk_bf16_f32 v156, v112, v113
	v_cvt_pk_bf16_f32 v157, v114, v115
	ds_read_b64_tr_b16 v[164:165], v4 offset:28672
	ds_read_b64_tr_b16 v[166:167], v4 offset:29184
	s_waitcnt lgkmcnt(10)
	v_mfma_f32_32x32x16_bf16 v[64:79], v[160:163], v[148:151], v[48:63]
	v_add_f32_e32 v2, v118, v2
	v_add_f32_e32 v2, v119, v2
	v_add_f32_e32 v2, v120, v2
	v_add_f32_e32 v2, v121, v2
	v_cvt_pk_bf16_f32 v158, v116, v117
	v_cvt_pk_bf16_f32 v159, v118, v119
	ds_read_b64_tr_b16 v[160:161], v4 offset:25600
	ds_read_b64_tr_b16 v[162:163], v4 offset:26112
	s_waitcnt lgkmcnt(11)
	v_mfma_f32_32x32x16_bf16 v[80:95], v[192:195], v[140:143], v[80:95]
	v_add_f32_e32 v2, v122, v2
	v_add_f32_e32 v2, v123, v2
	v_add_f32_e32 v2, v124, v2
	v_add_f32_e32 v2, v125, v2
	v_cvt_pk_bf16_f32 v152, v120, v121
	v_cvt_pk_bf16_f32 v153, v122, v123
	ds_read_b64_tr_b16 v[116:117], v4 offset:29696
	ds_read_b64_tr_b16 v[118:119], v4 offset:30208
	s_waitcnt lgkmcnt(12)
	v_mfma_f32_32x32x16_bf16 v[64:79], v[184:187], v[140:143], v[64:79]
	v_add_f32_e32 v2, v126, v2
	v_add_f32_e32 v2, v127, v2
	v_add_f32_e32 v2, v96, v2
	v_add_f32_e32 v2, v97, v2
	v_cvt_pk_bf16_f32 v154, v124, v125
	v_cvt_pk_bf16_f32 v155, v126, v127
	ds_read_b64_tr_b16 v[112:113], v4 offset:26624
	ds_read_b64_tr_b16 v[114:115], v4 offset:27136
	s_waitcnt lgkmcnt(13)
	v_mfma_f32_32x32x16_bf16 v[80:95], v[188:191], v[132:135], v[80:95]
	v_add_f32_e32 v2, v98, v2
	v_add_f32_e32 v2, v99, v2
	v_add_f32_e32 v2, v100, v2
	v_add_f32_e32 v2, v101, v2
	v_cvt_pk_bf16_f32 v144, v96, v97
	v_cvt_pk_bf16_f32 v145, v98, v99
	ds_read_b64_tr_b16 v[10:11], v4 offset:30720
	ds_read_b64_tr_b16 v[12:13], v4 offset:31232
	s_waitcnt lgkmcnt(14)
	v_mfma_f32_32x32x16_bf16 v[64:79], v[176:179], v[132:135], v[64:79]
	v_add_f32_e32 v2, v102, v2
	v_add_f32_e32 v2, v103, v2
	v_add_f32_e32 v2, v104, v2
	v_add_f32_e32 v2, v105, v2
	v_cvt_pk_bf16_f32 v146, v100, v101
	v_cvt_pk_bf16_f32 v147, v102, v103
	ds_read_b64_tr_b16 v[6:7], v4 offset:27648
	ds_read_b64_tr_b16 v[8:9], v4 offset:28160
	s_waitcnt lgkmcnt(14)
	v_mfma_f32_32x32x16_bf16 v[80:95], v[180:183], v[128:131], v[80:95]
	v_add_f32_e32 v2, v106, v2
	v_add_f32_e32 v2, v107, v2
	v_add_f32_e32 v2, v108, v2
	v_add_f32_e32 v15, v109, v2
	v_cvt_pk_bf16_f32 v136, v104, v105
	v_cvt_pk_bf16_f32 v137, v106, v107
	ds_read_b64_tr_b16 v[2:3], v4 offset:31744
	ds_read_b64_tr_b16 v[4:5], v4 offset:32256
	v_mfma_f32_32x32x16_bf16 v[64:79], v[172:175], v[128:131], v[64:79]
	v_add_f32_e32 v15, v110, v15
	v_add_f32_e32 v15, v111, v15
	v_cvt_pk_bf16_f32 v138, v108, v109
	v_cvt_pk_bf16_f32 v139, v110, v111
	s_cmp_lg_u32 s98, 0
	s_cbranch_scc1 .Lbm_skip_b
	v_max_f32_e32 v96, v81, v81
	v_max_f32_e32 v97, v80, v80
	v_max_f32_e32 v96, v97, v96
	s_nop 3
	s_nop 0
	v_max3_f32 v97, v82, v83, v65
	v_max3_f32 v96, v96, v64, v66
	v_max3_f32 v96, v96, v67, v84
	v_max3_f32 v97, v97, v86, v87
	v_max3_f32 v96, v96, v85, v68
	v_max3_f32 v97, v97, v70, v71
	v_max3_f32 v96, v96, v69, v88
	v_max3_f32 v97, v97, v90, v91
	v_max3_f32 v96, v96, v89, v72
	v_max3_f32 v97, v97, v74, v75
	v_max3_f32 v96, v96, v73, v92
	v_max3_f32 v97, v97, v94, v95
	v_max3_f32 v96, v96, v93, v76
	v_max3_f32 v97, v97, v78, v79
	v_add_f32_e32 v225, v14, v15
	v_max3_f32 v14, v96, v77, v97
	v_mov_b32_e32 v15, v14
	s_nop 1
	v_permlane32_swap_b32_e32 v14, v15
	s_add_i32 s10, s52, s15
	s_mov_b32 m0, s10
	s_nop 0
	global_load_lds_dwordx4 v[200:201], off
	s_lshl_b32 s10, s80, 1
	v_max_f32_e32 v14, v14, v15
	s_add_i32 s10, s10, s33
	s_mov_b32 m0, s10
	s_nop 0
	global_load_lds_dwordx4 v[198:199], off
	v_cmp_lt_f32_e32 vcc, s13, v14
	s_cmp_lg_u64 vcc, 0
	s_cselect_b64 s[10:11], -1, 0
	s_cbranch_vccnz .LBB0_499
	s_branch .LBB0_492
.Lbm_skip_b:
	v_add_f32_e32 v225, v14, v15
	s_add_i32 s10, s52, s15
	s_mov_b32 m0, s10
	s_nop 0
	global_load_lds_dwordx4 v[200:201], off
	s_lshl_b32 s10, s80, 1
	s_add_i32 s10, s10, s33
	s_mov_b32 m0, s10
	s_nop 0
	global_load_lds_dwordx4 v[198:199], off
	s_mov_b64 s[10:11], 0

;   #define RESC() do{ if(resc){ asm volatile("s_waitcnt lgkmcnt(0)":::"memory"); \
;       _Pragma("unroll") for(int d_=0;d_<ND;++d_) _Pragma("unroll") for(int r=0;r<16;++r)o[d_][r]*=wsf[crow(r,hi)]; } }while(0)
;   #define ROT() do{sl_prev=sl_cur;sl_cur=sl_next;sl_next=(sl_next==(NSLOT-1)*SLOTB)?0:sl_next+SLOTB;}while(0)
;   #define ENDW(tt) do{ if((tt)+3<NT){ if(MODE==2){WAIT_BAR(3);}else{WAIT_BAR(2);} } else if((tt)+2<NT){ if(MODE==2){WAIT_BAR(2);}else{WAIT_BAR(1);} } else {WAIT_BAR(0);} }while(0)
; template<int MODE,int THRL> __device__ __forceinline__ void attn_unit(const bf16*Qw0,int PQ,const bf16*__restrict__ Kh,int PK,const bf16*__restrict__ Vh,int PV,bf16*Ow0,int PO,int NT,int nabase,int nar0,const float*rpbh,char*shm,int&rot,bool pre,bool hasn,long dKn,long dVn){
;     ...
;   for(;t+1<NT;t+=2){
;     STEP(pB0,pB1,pA0,pA1,t,(t+3<NT),(t+1<NT),(t+1<NT));       ENDW(t);   RESC(); ROT();
;     STEP(pA0,pA1,pB0,pB1,t+1,(t+4<NT),(t+2<NT),(t+2<NT));     ENDW(t+1); RESC(); ROT();
.LBB0_508:
	v_lshl_add_u32 v0, s82, 1, v220
	ds_read_b64_tr_b16 v[196:197], v0 offset:24576
	ds_read_b64_tr_b16 v[198:199], v0 offset:25088
	s_waitcnt lgkmcnt(9)
	v_mfma_f32_32x32x16_bf16 v[112:127], v[188:191], v[148:151], v[48:63]
	v_add_f32_e32 v2, v80, v81
	v_add_f32_e32 v2, v82, v2
	v_add_f32_e32 v2, v83, v2
	v_add_f32_e32 v2, v84, v2
	v_add_f32_e32 v2, v85, v2
	v_cvt_pk_bf16_f32 v156, v80, v81
	v_cvt_pk_bf16_f32 v157, v82, v83
	ds_read_b64_tr_b16 v[188:189], v0 offset:28672
	ds_read_b64_tr_b16 v[190:191], v0 offset:29184
	s_waitcnt lgkmcnt(10)
	v_mfma_f32_32x32x16_bf16 v[96:111], v[184:187], v[148:151], v[48:63]
	v_add_f32_e32 v2, v86, v2
	v_add_f32_e32 v2, v87, v2
	v_add_f32_e32 v2, v88, v2
	v_add_f32_e32 v2, v89, v2
	v_cvt_pk_bf16_f32 v158, v84, v85
	v_cvt_pk_bf16_f32 v159, v86, v87
	ds_read_b64_tr_b16 v[192:193], v0 offset:25600
	ds_read_b64_tr_b16 v[194:195], v0 offset:26112
	s_waitcnt lgkmcnt(11)
	v_mfma_f32_32x32x16_bf16 v[112:127], v[180:183], v[140:143], v[112:127]
	v_add_f32_e32 v2, v90, v2
	v_add_f32_e32 v2, v91, v2
	v_add_f32_e32 v2, v92, v2
	v_add_f32_e32 v2, v93, v2
	v_cvt_pk_bf16_f32 v152, v88, v89
	v_cvt_pk_bf16_f32 v153, v90, v91
	ds_read_b64_tr_b16 v[84:85], v0 offset:29696
	ds_read_b64_tr_b16 v[86:87], v0 offset:30208
	s_waitcnt lgkmcnt(12)
	v_mfma_f32_32x32x16_bf16 v[96:111], v[176:179], v[140:143], v[96:111]
	v_add_f32_e32 v2, v94, v2
	v_add_f32_e32 v2, v95, v2
	v_add_f32_e32 v2, v64, v2
	v_add_f32_e32 v2, v65, v2
	v_cvt_pk_bf16_f32 v154, v92, v93
	v_cvt_pk_bf16_f32 v155, v94, v95
	ds_read_b64_tr_b16 v[80:81], v0 offset:26624
	ds_read_b64_tr_b16 v[82:83], v0 offset:27136
	s_waitcnt lgkmcnt(13)
	v_mfma_f32_32x32x16_bf16 v[112:127], v[172:175], v[132:135], v[112:127]
	v_add_f32_e32 v2, v66, v2
	v_add_f32_e32 v2, v67, v2
	v_add_f32_e32 v2, v68, v2
	v_add_f32_e32 v2, v69, v2
	v_cvt_pk_bf16_f32 v144, v64, v65
	v_cvt_pk_bf16_f32 v145, v66, v67
	ds_read_b64_tr_b16 v[10:11], v0 offset:30720
	ds_read_b64_tr_b16 v[12:13], v0 offset:31232
	s_waitcnt lgkmcnt(14)
	v_mfma_f32_32x32x16_bf16 v[96:111], v[168:171], v[132:135], v[96:111]
	v_add_f32_e32 v2, v70, v2
	v_add_f32_e32 v2, v71, v2
	v_add_f32_e32 v2, v72, v2
	v_add_f32_e32 v2, v73, v2
	v_cvt_pk_bf16_f32 v146, v68, v69
	v_cvt_pk_bf16_f32 v147, v70, v71
	ds_read_b64_tr_b16 v[6:7], v0 offset:27648
	ds_read_b64_tr_b16 v[8:9], v0 offset:28160
	s_waitcnt lgkmcnt(14)
	v_mfma_f32_32x32x16_bf16 v[112:127], v[164:167], v[128:131], v[112:127]
	v_add_f32_e32 v2, v74, v2
	v_add_f32_e32 v2, v75, v2
	v_add_f32_e32 v2, v76, v2
	v_add_f32_e32 v64, v77, v2
	v_cvt_pk_bf16_f32 v136, v72, v73
	v_cvt_pk_bf16_f32 v137, v74, v75
	ds_read_b64_tr_b16 v[2:3], v0 offset:31744
	ds_read_b64_tr_b16 v[4:5], v0 offset:32256
	v_mfma_f32_32x32x16_bf16 v[96:111], v[160:163], v[128:131], v[96:111]
	v_add_f32_e32 v0, v78, v64
	v_add_f32_e32 v0, v79, v0
	v_cvt_pk_bf16_f32 v138, v76, v77
	v_cvt_pk_bf16_f32 v139, v78, v79
	s_add_i32 s10, s86, 3
	s_cmp_ge_u32 s10, s39
	s_cselect_b64 s[78:79], -1, 0
	s_and_b64 vcc, exec, s[78:79]
	s_cbranch_vccnz .LBB0_510
	v_lshl_add_u64 v[64:65], v[208:209], 0, s[60:61]
	s_add_i32 s10, s43, s15
	s_mov_b32 m0, s10
	s_nop 0
	global_load_lds_dwordx4 v[64:65], off
.LBB0_510:
	v_add_f32_e32 v225, v225, v0
	v_max_f32_e32 v0, v112, v113
	v_max3_f32 v64, v114, v115, v97
	v_max3_f32 v0, v0, v96, v98
	v_max3_f32 v0, v0, v99, v116
	v_max3_f32 v64, v64, v118, v119
	v_max3_f32 v0, v0, v117, v100
	v_max3_f32 v64, v64, v102, v103
	v_max3_f32 v0, v0, v101, v120
	v_max3_f32 v64, v64, v122, v123
	v_max3_f32 v0, v0, v121, v104
	v_max3_f32 v64, v64, v106, v107
	v_max3_f32 v0, v0, v105, v124
	v_max3_f32 v64, v64, v126, v127
	v_max3_f32 v0, v0, v125, v108
	v_max3_f32 v64, v64, v110, v111
	v_max3_f32 v0, v0, v109, v64
	v_mov_b32_e32 v64, v0
	s_nop 1
	v_permlane32_swap_b32_e32 v0, v64
	s_lshl_b32 s89, s52, 1
	v_max_f32_e32 v0, v0, v64
	s_add_i32 s10, s89, s33
	s_mov_b32 m0, s10
	s_nop 0
	global_load_lds_dwordx4 v[14:15], off
	v_cmp_lt_f32_e32 vcc, s13, v0
	s_cmp_lg_u64 vcc, 0
	s_cselect_b64 s[10:11], -1, 0
	s_cbranch_vccnz .LBB0_546

;   #define RESC() do{ if(resc){ asm volatile("s_waitcnt lgkmcnt(0)":::"memory"); \
;       _Pragma("unroll") for(int d_=0;d_<ND;++d_) _Pragma("unroll") for(int r=0;r<16;++r)o[d_][r]*=wsf[crow(r,hi)]; } }while(0)
;   #define ROT() do{sl_prev=sl_cur;sl_cur=sl_next;sl_next=(sl_next==(NSLOT-1)*SLOTB)?0:sl_next+SLOTB;}while(0)
;   #define ENDW(tt) do{ if((tt)+3<NT){ if(MODE==2){WAIT_BAR(3);}else{WAIT_BAR(2);} } else if((tt)+2<NT){ if(MODE==2){WAIT_BAR(2);}else{WAIT_BAR(1);} } else {WAIT_BAR(0);} }while(0)
; template<int MODE,int THRL> __device__ __forceinline__ void attn_unit(const bf16*Qw0,int PQ,const bf16*__restrict__ Kh,int PK,const bf16*__restrict__ Vh,int PV,bf16*Ow0,int PO,int NT,int nabase,int nar0,const float*rpbh,char*shm,int&rot,bool pre,bool hasn,long dKn,long dVn){
;     ...
;   for(;t+1<NT;t+=2){
;     STEP(pB0,pB1,pA0,pA1,t,(t+3<NT),(t+1<NT),(t+1<NT));       ENDW(t);   RESC(); ROT();
;     STEP(pA0,pA1,pB0,pB1,t+1,(t+4<NT),(t+2<NT),(t+2<NT));     ENDW(t+1); RESC(); ROT();
;   }
.LBB0_519:
	v_lshl_add_u32 v4, s43, 1, v220
	ds_read_b64_tr_b16 v[200:201], v4 offset:24576
	ds_read_b64_tr_b16 v[202:203], v4 offset:25088
	s_waitcnt lgkmcnt(9)
	v_mfma_f32_32x32x16_bf16 v[80:95], v[188:191], v[148:151], v[48:63]
	v_add_f32_e32 v2, v112, v113
	v_add_f32_e32 v2, v114, v2
	v_add_f32_e32 v2, v115, v2
	v_add_f32_e32 v2, v116, v2
	v_add_f32_e32 v2, v117, v2
	v_cvt_pk_bf16_f32 v156, v112, v113
	v_cvt_pk_bf16_f32 v157, v114, v115
	ds_read_b64_tr_b16 v[196:197], v4 offset:28672
	ds_read_b64_tr_b16 v[198:199], v4 offset:29184
	s_waitcnt lgkmcnt(10)
	v_mfma_f32_32x32x16_bf16 v[64:79], v[184:187], v[148:151], v[48:63]
	v_add_f32_e32 v2, v118, v2
	v_add_f32_e32 v2, v119, v2
	v_add_f32_e32 v2, v120, v2
	v_add_f32_e32 v2, v121, v2
	v_cvt_pk_bf16_f32 v158, v116, v117
	v_cvt_pk_bf16_f32 v159, v118, v119
	ds_read_b64_tr_b16 v[192:193], v4 offset:25600
	ds_read_b64_tr_b16 v[194:195], v4 offset:26112
	s_waitcnt lgkmcnt(11)
	v_mfma_f32_32x32x16_bf16 v[80:95], v[180:183], v[140:143], v[80:95]
	v_add_f32_e32 v2, v122, v2
	v_add_f32_e32 v2, v123, v2
	v_add_f32_e32 v2, v124, v2
	v_add_f32_e32 v2, v125, v2
	v_cvt_pk_bf16_f32 v152, v120, v121
	v_cvt_pk_bf16_f32 v153, v122, v123
	ds_read_b64_tr_b16 v[116:117], v4 offset:29696
	ds_read_b64_tr_b16 v[118:119], v4 offset:30208
	s_waitcnt lgkmcnt(12)
	v_mfma_f32_32x32x16_bf16 v[64:79], v[176:179], v[140:143], v[64:79]
	v_add_f32_e32 v2, v126, v2
	v_add_f32_e32 v2, v127, v2
	v_add_f32_e32 v2, v96, v2
	v_add_f32_e32 v2, v97, v2
	v_cvt_pk_bf16_f32 v154, v124, v125
	v_cvt_pk_bf16_f32 v155, v126, v127
	ds_read_b64_tr_b16 v[112:113], v4 offset:26624
	ds_read_b64_tr_b16 v[114:115], v4 offset:27136
	s_waitcnt lgkmcnt(13)
	v_mfma_f32_32x32x16_bf16 v[80:95], v[172:175], v[132:135], v[80:95]
	v_add_f32_e32 v2, v98, v2
	v_add_f32_e32 v2, v99, v2
	v_add_f32_e32 v2, v100, v2
	v_add_f32_e32 v2, v101, v2
	v_cvt_pk_bf16_f32 v144, v96, v97
	v_cvt_pk_bf16_f32 v145, v98, v99
	ds_read_b64_tr_b16 v[10:11], v4 offset:30720
	ds_read_b64_tr_b16 v[12:13], v4 offset:31232
	s_waitcnt lgkmcnt(14)
	v_mfma_f32_32x32x16_bf16 v[64:79], v[168:171], v[132:135], v[64:79]
	v_add_f32_e32 v2, v102, v2
	v_add_f32_e32 v2, v103, v2
	v_add_f32_e32 v2, v104, v2
	v_add_f32_e32 v2, v105, v2
	v_cvt_pk_bf16_f32 v146, v100, v101
	v_cvt_pk_bf16_f32 v147, v102, v103
	ds_read_b64_tr_b16 v[6:7], v4 offset:27648
	ds_read_b64_tr_b16 v[8:9], v4 offset:28160
	s_waitcnt lgkmcnt(14)
	v_mfma_f32_32x32x16_bf16 v[80:95], v[164:167], v[128:131], v[80:95]
	v_add_f32_e32 v2, v106, v2
	v_add_f32_e32 v2, v107, v2
	v_add_f32_e32 v2, v108, v2
	v_add_f32_e32 v96, v109, v2
	v_cvt_pk_bf16_f32 v136, v104, v105
	v_cvt_pk_bf16_f32 v137, v106, v107
	ds_read_b64_tr_b16 v[2:3], v4 offset:31744
	ds_read_b64_tr_b16 v[4:5], v4 offset:32256
	v_mfma_f32_32x32x16_bf16 v[64:79], v[160:163], v[128:131], v[64:79]
	v_add_f32_e32 v96, v110, v96
	v_add_f32_e32 v96, v111, v96
	v_cvt_pk_bf16_f32 v138, v108, v109
	v_cvt_pk_bf16_f32 v139, v110, v111
	s_cmp_ge_u32 s86, s88
	s_cselect_b64 s[80:81], -1, 0
	s_and_b64 vcc, exec, s[80:81]
	s_cbranch_vccnz .LBB0_521
	s_add_i32 s10, s52, s15
	s_mov_b32 m0, s10
	s_nop 0
	global_load_lds_dwordx4 v[208:209], off
.LBB0_521:
	s_add_i32 s10, s52, 0x2000
	s_cmpk_lg_i32 s52, 0x4000
	s_cselect_b32 s43, s10, 0
	s_add_i32 s86, s86, 2
	s_cmp_lt_u32 s86, s39
	s_cselect_b64 s[84:85], -1, 0
	s_cmp_ge_u32 s86, s39
	s_cbranch_scc1 .LBB0_523
	s_lshl_b32 s10, s43, 1
	v_lshl_add_u64 v[98:99], v[14:15], 0, s[54:55]
	s_add_i32 s10, s10, s33
	s_mov_b32 m0, s10
	s_nop 0
	global_load_lds_dwordx4 v[98:99], off

;   #define RESC() do{ if(resc){ asm volatile("s_waitcnt lgkmcnt(0)":::"memory"); \
;       _Pragma("unroll") for(int d_=0;d_<ND;++d_) _Pragma("unroll") for(int r=0;r<16;++r)o[d_][r]*=wsf[crow(r,hi)]; } }while(0)
; template<int MODE,int THRL> __device__ __forceinline__ void attn_unit(const bf16*Qw0,int PQ,const bf16*__restrict__ Kh,int PK,const bf16*__restrict__ Vh,int PV,bf16*Ow0,int PO,int NT,int nabase,int nar0,const float*rpbh,char*shm,int&rot,bool pre,bool hasn,long dKn,long dVn){
;     ...
;   pfnow=hasn; STEP(pB0,pB1,pA0,pA1,NT-1,false,false,false); RESC(); pfnow=false;
.LBB0_554:
	v_add_u32_e32 v0, s89, v220
	ds_read_b64_tr_b16 v[120:121], v0 offset:24576
	ds_read_b64_tr_b16 v[122:123], v0 offset:25088
	s_waitcnt lgkmcnt(9)
	v_mfma_f32_32x32x16_bf16 v[96:111], v[188:191], v[148:151], v[48:63]
	v_add_f32_e32 v2, v80, v81
	v_add_f32_e32 v2, v82, v2
	v_add_f32_e32 v2, v83, v2
	v_add_f32_e32 v2, v84, v2
	v_add_f32_e32 v2, v85, v2
	v_cvt_pk_bf16_f32 v156, v80, v81
	v_cvt_pk_bf16_f32 v157, v82, v83
	ds_read_b64_tr_b16 v[116:117], v0 offset:28672
	ds_read_b64_tr_b16 v[118:119], v0 offset:29184
	s_waitcnt lgkmcnt(10)
	v_mfma_f32_32x32x16_bf16 v[48:63], v[184:187], v[148:151], v[48:63]
	v_add_f32_e32 v2, v86, v2
	v_add_f32_e32 v2, v87, v2
	v_add_f32_e32 v2, v88, v2
	v_add_f32_e32 v2, v89, v2
	v_cvt_pk_bf16_f32 v158, v84, v85
	v_cvt_pk_bf16_f32 v159, v86, v87
	ds_read_b64_tr_b16 v[112:113], v0 offset:25600
	ds_read_b64_tr_b16 v[114:115], v0 offset:26112
	s_waitcnt lgkmcnt(11)
	v_mfma_f32_32x32x16_bf16 v[96:111], v[180:183], v[140:143], v[96:111]
	v_add_f32_e32 v2, v90, v2
	v_add_f32_e32 v2, v91, v2
	v_add_f32_e32 v2, v92, v2
	v_add_f32_e32 v2, v93, v2
	v_cvt_pk_bf16_f32 v152, v88, v89
	v_cvt_pk_bf16_f32 v153, v90, v91
	ds_read_b64_tr_b16 v[84:85], v0 offset:29696
	ds_read_b64_tr_b16 v[86:87], v0 offset:30208
	s_waitcnt lgkmcnt(12)
	v_mfma_f32_32x32x16_bf16 v[48:63], v[176:179], v[140:143], v[48:63]
	v_add_f32_e32 v2, v94, v2
	v_add_f32_e32 v2, v95, v2
	v_add_f32_e32 v2, v64, v2
	v_add_f32_e32 v2, v65, v2
	v_cvt_pk_bf16_f32 v154, v92, v93
	v_cvt_pk_bf16_f32 v155, v94, v95
	ds_read_b64_tr_b16 v[80:81], v0 offset:26624
	ds_read_b64_tr_b16 v[82:83], v0 offset:27136
	s_waitcnt lgkmcnt(13)
	v_mfma_f32_32x32x16_bf16 v[96:111], v[172:175], v[132:135], v[96:111]
	v_add_f32_e32 v2, v66, v2
	v_add_f32_e32 v2, v67, v2
	v_add_f32_e32 v2, v68, v2
	v_add_f32_e32 v2, v69, v2
	v_cvt_pk_bf16_f32 v144, v64, v65
	v_cvt_pk_bf16_f32 v145, v66, v67
	ds_read_b64_tr_b16 v[10:11], v0 offset:30720
	ds_read_b64_tr_b16 v[12:13], v0 offset:31232
	s_waitcnt lgkmcnt(14)
	v_mfma_f32_32x32x16_bf16 v[48:63], v[168:171], v[132:135], v[48:63]
	v_add_f32_e32 v2, v70, v2
	v_add_f32_e32 v2, v71, v2
	v_add_f32_e32 v2, v72, v2
	v_add_f32_e32 v2, v73, v2
	v_cvt_pk_bf16_f32 v146, v68, v69
	v_cvt_pk_bf16_f32 v147, v70, v71
	ds_read_b64_tr_b16 v[6:7], v0 offset:27648
	ds_read_b64_tr_b16 v[8:9], v0 offset:28160
	s_waitcnt lgkmcnt(14)
	v_mfma_f32_32x32x16_bf16 v[96:111], v[164:167], v[128:131], v[96:111]
	v_add_f32_e32 v2, v74, v2
	v_add_f32_e32 v2, v75, v2
	v_add_f32_e32 v2, v76, v2
	v_add_f32_e32 v14, v77, v2
	v_cvt_pk_bf16_f32 v136, v72, v73
	v_cvt_pk_bf16_f32 v137, v74, v75
	ds_read_b64_tr_b16 v[2:3], v0 offset:31744
	ds_read_b64_tr_b16 v[4:5], v0 offset:32256
	v_mfma_f32_32x32x16_bf16 v[48:63], v[160:163], v[128:131], v[48:63]
	v_add_f32_e32 v0, v78, v14
	v_add_f32_e32 v0, v79, v0
	v_cvt_pk_bf16_f32 v138, v76, v77
	v_cvt_pk_bf16_f32 v139, v78, v79
	s_and_b64 vcc, exec, s[6:7]
	s_cbranch_vccnz .LBB0_556
	s_sub_u32 s6, s74, s70
	s_subb_u32 s7, s75, s71
	s_sub_u32 s10, s76, s72
	s_subb_u32 s11, s77, s73
	v_lshl_add_u64 v[14:15], v[204:205], 0, s[6:7]
	s_add_i32 s6, s82, s15
	s_mov_b32 m0, s6
	s_nop 0
	global_load_lds_dwordx4 v[14:15], off
	s_lshl_b32 s6, s82, 1
	v_lshl_add_u64 v[64:65], v[206:207], 0, s[10:11]
	s_add_i32 s6, s6, s33
	s_mov_b32 m0, s6
	s_nop 0
	global_load_lds_dwordx4 v[64:65], off
	v_lshl_add_u64 v[64:65], v[14:15], 0, s[54:55]
	s_add_i32 s6, s8, s15
	s_mov_b32 m0, s6
	s_nop 0
	global_load_lds_dwordx4 v[64:65], off
	v_lshl_add_u64 v[14:15], v[14:15], 0, s[56:57]
	s_add_i32 s6, s43, s15
	s_mov_b32 m0, s6
	s_nop 0
	global_load_lds_dwordx4 v[14:15], off

;   #define DMA_K(t,slot) glds16(ksrc+(long)KROW(t)*PK,(unsigned)__builtin_amdgcn_readfirstlane(kdst+(slot)))
;   #define DMA_V(t,slot) do{ glds16(vsrc+(long)KROW(t)*PV,(unsigned)__builtin_amdgcn_readfirstlane(vdst+2*(slot))); if(MODE==2)glds16(vsrc+(long)KROW(t)*PV+64,(unsigned)__builtin_amdgcn_readfirstlane(vdst+2*(slot)+SLOTB)); }while(0)
; template<int MODE,int THRL> __device__ __forceinline__ void attn_unit(const bf16*Qw0,int PQ,const bf16*__restrict__ Kh,int PK,const bf16*__restrict__ Vh,int PV,bf16*Ow0,int PO,int NT,int nabase,int nar0,const float*rpbh,char*shm,int&rot,bool pre,bool hasn,long dKn,long dVn){
;     ...
;   int tid_=threadIdx.x; asm volatile("":"+v"(tid_));
;   const int tid=tid_,lane=tid&63,r32=lane&31,hi=lane>>5; const int wid=__builtin_amdgcn_readfirstlane(tid>>6);
;   const bf16*Qw=Qw0+(long)wid*QBLK*PQ;
;   const unsigned lds0=(unsigned)(uintptr_t)shm;
;   float*wsf=(float*)(shm+LDS_WS)+wid*64;
;   const bf16*ksrc=Kh+(long)lane*PK+wid*8;
;   const bf16*vsrc=Vh+(long)(16*(wid&3)+(lane>>2))*PV+(wid>>2)*32+(lane&3)*8;
;   const unsigned kdst=lds0+LDS_K+wid*1024, vdst=lds0+LDS_V+wid*1024;
;     ...
;   const int vb0=(int)(lds0+LDS_V)+((lane>>4)&1)*32+(lane&3)*8+(4*hi+((lane&15)>>2))*64;
;   const char*Kbase=shm+LDS_K; bf16x8 kf[8];
;   const lds_cptr shm3=(lds_cptr)shm; const lds_cptr kp0=shm3+LDS_K+hi*1024+r32*16; const lds_cptr vp0=shm3+LDS_V+((lane>>4)&1)*32+(lane&3)*8+(4*hi+((lane&15)>>2))*64;
;   const lds_cfptr tb=(lds_cfptr)(shm3+LDS_TB);
;   u32x4_t mf[4];
;   const int nar=nar0+(wid>>1), nac=(wid&1)*32+r32;
;   if(!pre){ DMA_K(0,rot);DMA_V(0,rot);DMA_K(1,NXT(rot)); }
; template <int l> __device__ __forceinline__ void layer_body(const Args& a, unsigned char* lds, const XcdBarrier& bar, int G, int bx, int vcu, int gw, int NGW, int lane_, int tid_k, int wave) {
;     ...
;                     if (ok) { const int bh = g >> 6, b = bh >> 3, h = bh & 7, sub = g & 63, map = sub >> 5, qb = sub & 31;
;                         const size_t rb = (size_t)b * TPB, rq = rb + CTXL + (size_t)qb * 256;
;                         attn_body::attn_unit<2, 8>(qkv + rq * DIFF_IN + h * 128 + map * 64, DIFF_IN, qkv + rb * DIFF_IN + 1024 + h * 128 + map * 64, DIFF_IN, qkv + rb * DIFF_IN + 2048 + h * 128, DIFF_IN,
.LBB0_1117:
	s_ashr_i32 s76, s96, 9
	s_lshl_b32 s1, s96, 1
	s_mul_hi_i32 s83, s76, 0x18c0000
	s_mul_i32 s82, s76, 0x18c0000
	s_xor_b64 s[6:7], s[6:7], -1
	s_bfe_u32 s73, s96, 0x10005
	s_and_b32 s80, s1, 0x380
	s_lshl_b64 s[10:11], s[82:83], 1
	s_add_u32 s1, s44, s10
	s_addc_u32 s3, s45, s11
	s_lshl_b32 s4, s80, 1
	s_add_u32 s10, s1, s4
	s_addc_u32 s11, s3, 0
	s_lshl_b32 s1, s73, 7
	v_mov_b32_e32 v40, v222
	s_add_u32 s70, s10, s1
	s_addc_u32 s71, s11, 0
	v_and_b32_e32 v237, 63, v40
	v_readfirstlane_b32 s3, v40
	s_ashr_i32 s74, s3, 6
	v_mul_u32_u24_e32 v1, 0xc00, v237
	v_lshlrev_b32_e32 v34, 1, v1
	s_lshl_b32 s1, s74, 4
	v_bfe_u32 v1, v40, 2, 4
	v_and_or_b32 v1, s1, 48, v1
	s_mov_b32 s0, s86
	v_mov_b32_e32 v35, v0
	s_lshl_b32 s86, s74, 3
	v_mul_u32_u24_e32 v1, 0xc00, v1
	s_ashr_i32 s1, s3, 3
	v_lshl_add_u64 v[2:3], s[70:71], 0, v[34:35]
	s_ashr_i32 s87, s86, 31
	v_lshlrev_b32_e32 v36, 1, v1
	v_mov_b32_e32 v37, v0
	s_and_b32 s88, s1, 0xffffffe0
	v_lshlrev_b32_e32 v238, 3, v40
	v_lshl_add_u64 v[220:221], s[86:87], 1, v[2:3]
	v_lshl_add_u64 v[2:3], s[10:11], 0, v[36:37]
	s_ashr_i32 s89, s88, 31
	v_and_b32_e32 v241, 24, v238
	v_lshl_add_u64 v[2:3], s[88:89], 1, v[2:3]
	v_lshlrev_b32_e32 v4, 1, v241
	v_mov_b32_e32 v5, v0
	s_mov_b64 s[70:71], 0x800
	v_lshl_add_u64 v[2:3], v[2:3], 0, v[4:5]
	s_mov_b64 s[10:11], 0x1000
	s_lshl_b32 s55, s74, 10
	v_lshl_add_u64 v[38:39], v[220:221], 0, s[70:71]
	v_lshl_add_u64 v[224:225], v[2:3], 0, s[10:11]
	s_add_i32 s1, s55, 0x6000
	s_mov_b64 s[70:71], -1
	s_and_b64 vcc, exec, s[6:7]
	s_cbranch_vccz .LBB0_1119
	s_add_i32 s4, s55, s9
	s_mov_b32 m0, s4
	s_nop 0
	global_load_lds_dwordx4 v[38:39], off
	s_lshl_b32 s4, s9, 1
	s_add_i32 s4, s1, s4
	s_mov_b32 m0, s4
	s_nop 0
	global_load_lds_dwordx4 v[224:225], off
	s_mov_b64 s[10:11], 0x80
	s_addk_i32 s4, 0x2000
	v_lshl_add_u64 v[2:3], v[224:225], 0, s[10:11]
	s_mov_b32 m0, s4
	s_nop 0
	global_load_lds_dwordx4 v[2:3], off
	s_add_i32 s4, s9, 0x2000
	s_cmpk_lg_i32 s9, 0x4000
	s_cselect_b32 s8, s4, 0
	v_lshl_add_u64 v[2:3], v[38:39], 0, s[58:59]
	s_add_i32 s8, s55, s8
	s_mov_b32 m0, s8
	s_nop 0
	global_load_lds_dwordx4 v[2:3], off
	s_mov_b64 s[70:71], 0

; #define WAIT_BAR(N) asm volatile("s_waitcnt vmcnt(" #N ") lgkmcnt(0)\n\ts_barrier":::"memory")
;   #define DMA_K(t,slot) glds16(ksrc+(long)KROW(t)*PK,(unsigned)__builtin_amdgcn_readfirstlane(kdst+(slot)))
; template<int MODE,int THRL> __device__ __forceinline__ void attn_unit(const bf16*Qw0,int PQ,const bf16*__restrict__ Kh,int PK,const bf16*__restrict__ Vh,int PV,bf16*Ow0,int PO,int NT,int nabase,int nar0,const float*rpbh,char*shm,int&rot,bool pre,bool hasn,long dKn,long dVn){
;     ...
;   bf16x8 qr[4];
;   #pragma unroll
;   for(int d0=0;d0<4;++d0)qr[d0]=*reinterpret_cast<const bf16x8*>(&Qw[(long)r32*PQ+d0*16+hi*8]);
;   float mhat=0.f,l_reg=0.f;constexpr int ND=(MODE==2)?4:2; f32x16 o[4];o[0]=f32x16{};o[1]=f32x16{};o[2]=f32x16{};o[3]=f32x16{};f32x16 negm=f32x16{};asm volatile("":"+v"(negm));
;     ...
;   bool resc=false;
;     ...
;   f32x16 pA0,pA1,pB0,pB1;
;   int sl_prev=rot,sl_cur=rot,sl_next=NXT(rot);
;   bool pfnow=false;
;     ...
;   if(!pre){ DMA_K(2,NXT(sl_next)); }
;   if(pre){WAIT_BAR(0);}else if(MODE==2){WAIT_BAR(4);}else{WAIT_BAR(3);}
.LBB0_1121:
	s_lshl_b32 s15, s96, 8
	s_ashr_i32 s77, s76, 31
	s_lshl_b32 s10, s73, 6
	s_mul_i32 s11, s76, 0x2100
	s_and_b32 s78, s15, 0x1f00
	s_mul_hi_i32 s8, s76, 0x2100
	s_add_u32 s11, s11, s78
	s_addc_u32 s8, s8, 0
	s_add_u32 s70, s11, 0x100
	s_addc_u32 s71, s8, 0
	s_mul_i32 s8, s71, 0x1800
	s_mul_hi_u32 s11, s70, 0x1800
	s_add_i32 s11, s11, s8
	s_mul_i32 s8, s70, 0x1800
	s_add_u32 s8, s44, s8
	s_addc_u32 s11, s45, s11
	s_lshl_b32 s72, s80, 1
	s_add_u32 s8, s8, s72
	s_addc_u32 s11, s11, 0
	s_lshl_b32 s15, s10, 1
	s_add_u32 s8, s8, s15
	v_and_b32_e32 v239, 31, v40
	s_addc_u32 s11, s11, 0
	s_mul_i32 s33, s74, 0x30000
	v_mul_u32_u24_e32 v1, 0xc00, v239
	v_lshrrev_b32_e32 v240, 5, v237
	s_mul_hi_i32 s15, s74, 0x30000
	s_add_u32 s90, s8, s33
	v_lshlrev_b32_e32 v1, 1, v1
	s_addc_u32 s91, s11, s15
	v_lshl_or_b32 v1, v240, 4, v1
	global_load_dwordx4 v[174:177], v1, s[90:91]
	global_load_dwordx4 v[170:173], v1, s[90:91] offset:32
	global_load_dwordx4 v[166:169], v1, s[90:91] offset:64
	global_load_dwordx4 v[162:165], v1, s[90:91] offset:96
	v_mov_b32_e32 v2, v0
	v_mov_b32_e32 v3, v0
	v_mov_b32_e32 v4, v0
	v_mov_b32_e32 v5, v0
	v_mov_b32_e32 v6, v0
	v_mov_b32_e32 v7, v0
	v_mov_b32_e32 v8, v0
	v_mov_b32_e32 v9, v0
	v_mov_b32_e32 v10, v0
	v_mov_b32_e32 v11, v0
	v_mov_b32_e32 v12, v0
	v_mov_b32_e32 v13, v0
	v_mov_b32_e32 v14, v0
	v_mov_b32_e32 v15, v0
	v_mov_b32_e32 v1, v0
	v_mov_b64_e32 v[16:17], v[14:15]
	s_cmpk_lg_i32 s9, 0x4000
	s_mov_b32 s81, s85
	s_mov_b32 s11, s85
	s_mov_b32 s79, s85
	v_mov_b64_e32 v[14:15], v[12:13]
	v_mov_b64_e32 v[12:13], v[10:11]
	v_mov_b64_e32 v[10:11], v[8:9]
	v_mov_b64_e32 v[8:9], v[6:7]
	v_mov_b64_e32 v[6:7], v[4:5]
	v_mov_b64_e32 v[4:5], v[2:3]
	v_mov_b64_e32 v[2:3], v[0:1]
	s_cselect_b32 s15, s4, 0
	s_andn2_b64 vcc, exec, s[6:7]
	s_mov_b64 s[6:7], -1
	s_cbranch_vccnz .LBB0_1123
	s_add_i32 s4, s15, 0x2000
	s_cmpk_lg_i32 s15, 0x4000
	s_cselect_b32 s6, s4, 0
	v_lshl_add_u64 v[18:19], v[38:39], 0, s[60:61]
	s_add_i32 s6, s6, s55
	s_mov_b32 m0, s6
	s_nop 0
	global_load_lds_dwordx4 v[18:19], off
	s_waitcnt vmcnt(4) lgkmcnt(0)
	s_barrier
	s_mov_b64 s[6:7], 0

; #define WAIT_BAR(N) asm volatile("s_waitcnt vmcnt(" #N ") lgkmcnt(0)\n\ts_barrier":::"memory")
;   #define DMA_K(t,slot) glds16(ksrc+(long)KROW(t)*PK,(unsigned)__builtin_amdgcn_readfirstlane(kdst+(slot)))
;   #define DMA_V(t,slot) do{ glds16(vsrc+(long)KROW(t)*PV,(unsigned)__builtin_amdgcn_readfirstlane(vdst+2*(slot))); if(MODE==2)glds16(vsrc+(long)KROW(t)*PV+64,(unsigned)__builtin_amdgcn_readfirstlane(vdst+2*(slot)+SLOTB)); }while(0)
;   #define CMASK(P0,P1,t) do{ if(MODE==1&&(t)>=4)na_apply(P0,P1,mf,na_rowok((t),nabase,nar)); }while(0)
;   #define ROT() do{sl_prev=sl_cur;sl_cur=sl_next;sl_next=(sl_next==(NSLOT-1)*SLOTB)?0:sl_next+SLOTB;}while(0)
; __device__ __forceinline__ void qkt(f32x16&p0,f32x16&p1,const char*Kslot,const bf16x8*qr,const f32x16&negm,int r32,int hi){
;   const char*kb=Kslot+hi*1024+r32*16;
;   #pragma unroll
;   for(int d0=0;d0<4;++d0){
;     const bf16x8 b0=*reinterpret_cast<const bf16x8*>(kb+d0*2048);
;     const bf16x8 b1=*reinterpret_cast<const bf16x8*>(kb+d0*2048+512);
;     if(d0==0){p0=__builtin_amdgcn_mfma_f32_32x32x16_bf16(b0,qr[0],negm,0,0,0);p1=__builtin_amdgcn_mfma_f32_32x32x16_bf16(b1,qr[0],negm,0,0,0);}
;     else{p0=__builtin_amdgcn_mfma_f32_32x32x16_bf16(b0,qr[d0],p0,0,0,0);p1=__builtin_amdgcn_mfma_f32_32x32x16_bf16(b1,qr[d0],p1,0,0,0);}}
; template<int MODE,int THRL> __device__ __forceinline__ void attn_unit(const bf16*Qw0,int PQ,const bf16*__restrict__ Kh,int PK,const bf16*__restrict__ Vh,int PV,bf16*Ow0,int PO,int NT,int nabase,int nar0,const float*rpbh,char*shm,int&rot,bool pre,bool hasn,long dKn,long dVn){
;     ...
;   f32x16 pA0,pA1,pB0,pB1;
;   int sl_prev=rot,sl_cur=rot,sl_next=NXT(rot);
;   bool pfnow=false;
;     ...
;   if(!pre){ DMA_K(2,NXT(sl_next)); }
;   if(pre){WAIT_BAR(0);}else if(MODE==2){WAIT_BAR(4);}else{WAIT_BAR(3);}
;   qkt(pA0,pA1,Kbase+sl_cur,qr,negm,r32,hi);asm volatile("s_nop 15\n\ts_nop 7":"+v"(pA0),"+v"(pA1));CMASK(pA0,pA1,0);
;   START(pA0,pA1);
;   _Pragma("unroll") for(int r=0;r<16;++r)pA1[r]=__builtin_amdgcn_exp2f(pA1[r]);
;   WAIT_BAR(0);
;   DMA_K(3,sl_cur);DMA_V(1,sl_next);
;   ROT();
;   kload8(kf,kp0+sl_cur);
;   if(MODE==2){WAIT_BAR(3);}else{WAIT_BAR(2);}
.LBB0_1125:
	v_lshlrev_b32_e32 v1, 10, v240
	v_lshlrev_b32_e32 v35, 4, v239
	v_add3_u32 v37, s9, v1, v35
	ds_read_b128 v[42:45], v37
	v_or_b32_e32 v248, v1, v35
	s_add_i32 s6, s55, s9
	s_and_b32 s3, s3, 0x3fffffc0
	s_lshl_b32 s3, s3, 2
	s_ashr_i32 s75, s74, 31
	s_add_i32 s3, s3, 0x12000
	s_mul_i32 s8, s76, 0x3180000
	s_waitcnt vmcnt(3) lgkmcnt(0)
	v_mfma_f32_32x32x16_bf16 v[18:33], v[42:45], v[174:177], v[2:17]
	ds_read_b128 v[42:45], v37 offset:512
	v_lshl_or_b32 v243, v239, 2, s3
	v_lshlrev_b32_e32 v245, 4, v240
	v_mov_b32_e32 v249, 0
	s_waitcnt lgkmcnt(0)
	v_mfma_f32_32x32x16_bf16 v[2:17], v[42:45], v[174:177], v[2:17]
	ds_read_b128 v[42:45], v37 offset:2048
	s_waitcnt vmcnt(2) lgkmcnt(0)
	v_mfma_f32_32x32x16_bf16 v[18:33], v[42:45], v[170:173], v[18:33]
	ds_read_b128 v[42:45], v37 offset:2560
	s_waitcnt lgkmcnt(0)
	v_mfma_f32_32x32x16_bf16 v[2:17], v[42:45], v[170:173], v[2:17]
	ds_read_b128 v[42:45], v37 offset:4096
	s_waitcnt vmcnt(1) lgkmcnt(0)
	v_mfma_f32_32x32x16_bf16 v[18:33], v[42:45], v[166:169], v[18:33]
	ds_read_b128 v[42:45], v37 offset:4608
	s_waitcnt lgkmcnt(0)
	v_mfma_f32_32x32x16_bf16 v[2:17], v[42:45], v[166:169], v[2:17]
	ds_read_b128 v[42:45], v37 offset:6144
	ds_read_b128 v[46:49], v37 offset:6656
	v_lshlrev_b32_e32 v37, 1, v40
	v_and_b32_e32 v244, 32, v37
	v_lshlrev_b32_e32 v37, 4, v40
	v_and_b32_e32 v37, 0xc0, v37
	v_lshl_or_b32 v242, v240, 8, v37
	v_mov_b32_e32 v37, v0
	s_waitcnt vmcnt(0) lgkmcnt(1)
	v_mfma_f32_32x32x16_bf16 v[18:33], v[42:45], v[162:165], v[18:33]
	v_or3_b32 v247, v244, v241, v242
	s_waitcnt lgkmcnt(0)
	v_mfma_f32_32x32x16_bf16 v[2:17], v[46:49], v[162:165], v[2:17]
	s_nop 15
	s_nop 7
	s_nop 0
	v_max3_f32 v1, v18, v19, v2
	v_max3_f32 v35, v20, v21, v3
	s_nop 0
	v_max3_f32 v1, v1, v4, v5
	v_max3_f32 v35, v35, v24, v25
	s_nop 0
	v_max3_f32 v1, v1, v22, v23
	v_max3_f32 v35, v35, v8, v9
	s_nop 0
	v_max3_f32 v1, v1, v6, v7
	v_max3_f32 v35, v35, v28, v29
	s_nop 0
	v_max3_f32 v1, v1, v26, v27
	v_max3_f32 v35, v35, v12, v13
	s_nop 0
	v_max3_f32 v1, v1, v10, v11
	v_max3_f32 v35, v35, v32, v33
	s_nop 0
	v_max3_f32 v1, v1, v30, v31
	v_max3_f32 v35, v35, v16, v17
	s_nop 0
	v_max3_f32 v1, v1, v14, v15
	s_nop 0
	v_max_f32_e32 v1, v1, v35
	s_nop 0
	v_mov_b32_e32 v35, v1
	s_nop 1
	v_permlane32_swap_b32_e32 v1, v35
	v_max_f32_e32 v1, v1, v35
	v_mov_b32_e32 v35, v0
	v_add_f32_e32 v246, v0, v1
	v_sub_f32_e32 v2, v2, v1
	v_sub_f32_e32 v3, v3, v1
	v_sub_f32_e32 v18, v18, v1
	v_sub_f32_e32 v19, v19, v1
	v_sub_f32_e32 v20, v20, v1
	s_nop 0
	v_xor_b32_e32 v66, 0x80000000, v246
	v_mov_b32_e32 v67, v66
	v_mov_b32_e32 v68, v66
	v_mov_b32_e32 v69, v66
	v_mov_b32_e32 v70, v66
	v_mov_b32_e32 v71, v66
	v_mov_b32_e32 v72, v66
	v_mov_b32_e32 v73, v66
	v_mov_b32_e32 v74, v66
	v_mov_b32_e32 v75, v66
	v_mov_b32_e32 v76, v66
	v_mov_b32_e32 v77, v66
	v_mov_b32_e32 v78, v66
	v_mov_b32_e32 v79, v66
	v_mov_b32_e32 v80, v66
	v_mov_b32_e32 v81, v66
	s_waitcnt vmcnt(0) lgkmcnt(0)
	s_barrier
	v_exp_f32_e32 v82, v2
	v_exp_f32_e32 v83, v3
	v_lshl_add_u64 v[2:3], v[38:39], 0, s[62:63]
	s_mov_b32 m0, s6
	s_nop 0
	global_load_lds_dwordx4 v[2:3], off
	s_lshl_b32 s6, s15, 1
	s_add_i32 s6, s6, s1
	v_lshl_add_u64 v[2:3], v[224:225], 0, s[58:59]
	s_mov_b32 m0, s6
	s_nop 0
	global_load_lds_dwordx4 v[2:3], off
	s_addk_i32 s6, 0x2000
	s_cmpk_lg_i32 s15, 0x4000
	s_cselect_b32 s84, s4, 0
	s_lshl_b32 s33, s96, 2
	v_sub_f32_e32 v4, v4, v1
	v_sub_f32_e32 v21, v21, v1
	v_sub_f32_e32 v5, v5, v1
	v_sub_f32_e32 v22, v22, v1
	v_sub_f32_e32 v6, v6, v1
	v_sub_f32_e32 v23, v23, v1
	v_sub_f32_e32 v7, v7, v1
	v_sub_f32_e32 v24, v24, v1
	v_sub_f32_e32 v8, v8, v1
	v_sub_f32_e32 v25, v25, v1
	v_sub_f32_e32 v9, v9, v1
	v_sub_f32_e32 v26, v26, v1
	v_sub_f32_e32 v10, v10, v1
	v_sub_f32_e32 v27, v27, v1
	v_sub_f32_e32 v11, v11, v1
	v_sub_f32_e32 v28, v28, v1
	v_sub_f32_e32 v12, v12, v1
	v_sub_f32_e32 v29, v29, v1
	v_sub_f32_e32 v13, v13, v1
	v_sub_f32_e32 v30, v30, v1
	v_sub_f32_e32 v14, v14, v1
	v_sub_f32_e32 v31, v31, v1
	v_sub_f32_e32 v15, v15, v1
	v_sub_f32_e32 v32, v32, v1
	v_sub_f32_e32 v16, v16, v1
	v_sub_f32_e32 v33, v33, v1
	v_sub_f32_e32 v1, v17, v1
	s_and_b32 s90, s33, 0x700
	v_exp_f32_e32 v97, v1
	v_lshl_add_u64 v[2:3], v[224:225], 0, s[64:65]
	s_mov_b32 m0, s6
	s_nop 0
	global_load_lds_dwordx4 v[2:3], off
	v_add_u32_e32 v1, s15, v248
	s_or_b32 s8, s8, s90
	s_and_b32 s33, s33, 0x80
	ds_read_b128 v[206:209], v1
	ds_read_b128 v[198:201], v1 offset:512
	ds_read_b128 v[202:205], v1 offset:2048
	ds_read_b128 v[194:197], v1 offset:2560
	ds_read_b128 v[190:193], v1 offset:4096
	ds_read_b128 v[186:189], v1 offset:4608
	ds_read_b128 v[182:185], v1 offset:6144
	ds_read_b128 v[178:181], v1 offset:6656
	s_or_b32 s33, s8, s33
	s_lshl_b64 s[86:87], s[86:87], 1
	s_mul_hi_i32 s4, s76, 0x3180000
	s_add_u32 s86, s33, s86
	s_addc_u32 s87, s4, s87
	v_lshl_add_u64 v[210:211], s[86:87], 0, v[34:35]
	s_lshl_b64 s[86:87], s[88:89], 1
	v_and_b32_e32 v1, 3, v40
	s_add_u32 s86, s86, s8
	v_lshlrev_b32_e32 v2, 4, v1
	v_mov_b32_e32 v3, v0
	s_addc_u32 s87, s87, s4
	v_lshl_add_u64 v[2:3], s[86:87], 0, v[2:3]
	v_exp_f32_e32 v98, v18
	v_exp_f32_e32 v99, v19
	v_exp_f32_e32 v100, v20
	v_exp_f32_e32 v101, v21
	v_exp_f32_e32 v102, v22
	v_exp_f32_e32 v103, v23
	v_exp_f32_e32 v104, v24
	v_exp_f32_e32 v105, v25
	v_exp_f32_e32 v106, v26
	v_exp_f32_e32 v107, v27
	v_exp_f32_e32 v108, v28
	v_exp_f32_e32 v109, v29
	v_exp_f32_e32 v110, v30
	v_exp_f32_e32 v111, v31
	v_exp_f32_e32 v112, v32
	v_exp_f32_e32 v113, v33
	v_exp_f32_e32 v84, v4
	v_exp_f32_e32 v85, v5
	v_exp_f32_e32 v86, v6
	v_exp_f32_e32 v87, v7
	v_exp_f32_e32 v88, v8
	v_exp_f32_e32 v89, v9
	v_exp_f32_e32 v90, v10
	v_exp_f32_e32 v91, v11
	v_exp_f32_e32 v92, v12
	v_exp_f32_e32 v93, v13
	v_exp_f32_e32 v94, v14
	v_exp_f32_e32 v95, v15
	v_exp_f32_e32 v96, v16
	v_lshl_add_u64 v[2:3], v[2:3], 0, v[36:37]
	v_mov_b32_e32 v14, v0
	v_mov_b32_e32 v15, v0
	s_waitcnt vmcnt(3) lgkmcnt(0)
	s_barrier
; #define WAIT_BAR(N) asm volatile("s_waitcnt vmcnt(" #N ") lgkmcnt(0)\n\ts_barrier":::"memory")
;   #define RESC() do{ if(resc){ asm volatile("s_waitcnt lgkmcnt(0)":::"memory"); \
;       _Pragma("unroll") for(int d_=0;d_<ND;++d_) _Pragma("unroll") for(int r=0;r<16;++r)o[d_][r]*=wsf[crow(r,hi)]; } }while(0)
;   #define ROT() do{sl_prev=sl_cur;sl_cur=sl_next;sl_next=(sl_next==(NSLOT-1)*SLOTB)?0:sl_next+SLOTB;}while(0)
; template<int MODE,int THRL> __device__ __forceinline__ void attn_unit(const bf16*Qw0,int PQ,const bf16*__restrict__ Kh,int PK,const bf16*__restrict__ Vh,int PV,bf16*Ow0,int PO,int NT,int nabase,int nar0,const float*rpbh,char*shm,int&rot,bool pre,bool hasn,long dKn,long dVn){
;     ...
;   for(;t+5<NT;t+=2){
;     STEP(pB0,pB1,pA0,pA1,t,true,true,true);     if(MODE==2){WAIT_BAR(3);}else{WAIT_BAR(2);} RESC(); ROT();
;     STEP(pA0,pA1,pB0,pB1,t+1,true,true,true);   if(MODE==2){WAIT_BAR(3);}else{WAIT_BAR(2);} RESC(); ROT();
	v_lshl_add_u64 v[214:215], s[50:51], 0, v[2:3]
	v_mov_b32_e32 v1, v0
	v_mov_b32_e32 v2, v0
	v_mov_b32_e32 v3, v0
	v_mov_b32_e32 v4, v0
	v_mov_b32_e32 v5, v0
	v_mov_b32_e32 v6, v0
	v_mov_b32_e32 v7, v0
	v_mov_b32_e32 v8, v0
	v_mov_b32_e32 v9, v0
	v_mov_b32_e32 v10, v0
	v_mov_b32_e32 v11, v0
	v_mov_b32_e32 v12, v0
	v_mov_b32_e32 v13, v0
	v_mov_b64_e32 v[64:65], v[14:15]
	v_mov_b64_e32 v[48:49], v[14:15]
	v_mov_b64_e32 v[32:33], v[14:15]
	v_mov_b64_e32 v[62:63], v[12:13]
	v_mov_b64_e32 v[60:61], v[10:11]
	v_mov_b64_e32 v[58:59], v[8:9]
	v_mov_b64_e32 v[56:57], v[6:7]
	v_mov_b64_e32 v[54:55], v[4:5]
	v_mov_b64_e32 v[52:53], v[2:3]
	v_mov_b64_e32 v[50:51], v[0:1]
	v_mov_b64_e32 v[46:47], v[12:13]
	v_mov_b64_e32 v[44:45], v[10:11]
	v_mov_b64_e32 v[42:43], v[8:9]
	v_mov_b64_e32 v[40:41], v[6:7]
	v_mov_b64_e32 v[38:39], v[4:5]
	v_mov_b64_e32 v[36:37], v[2:3]
	v_mov_b64_e32 v[34:35], v[0:1]
	v_mov_b64_e32 v[30:31], v[12:13]
	v_mov_b64_e32 v[28:29], v[10:11]
	v_mov_b64_e32 v[26:27], v[8:9]
	v_mov_b64_e32 v[24:25], v[6:7]
	v_mov_b64_e32 v[22:23], v[4:5]
	v_mov_b64_e32 v[20:21], v[2:3]
	v_mov_b64_e32 v[18:19], v[0:1]
	v_mov_b64_e32 v[16:17], v[14:15]
	v_cmp_gt_u32_e64 s[6:7], 32, v237
	v_lshl_add_u64 v[212:213], s[40:41], 0, v[210:211]
	s_mov_b32 s90, -1
	v_mov_b64_e32 v[14:15], v[12:13]
	v_mov_b64_e32 v[12:13], v[10:11]
	v_mov_b64_e32 v[10:11], v[8:9]
	v_mov_b64_e32 v[8:9], v[6:7]
	v_mov_b64_e32 v[6:7], v[4:5]
	v_mov_b64_e32 v[4:5], v[2:3]
	v_mov_b64_e32 v[2:3], v[0:1]
.LBB0_1126:
	s_lshl_b32 s4, s9, 1
	v_add_u32_e32 v216, s4, v247
	ds_read_b64_tr_b16 v[226:227], v216 offset:24576
	ds_read_b64_tr_b16 v[228:229], v216 offset:25088
	s_waitcnt lgkmcnt(9)
	v_mfma_f32_32x32x16_bf16 v[130:145], v[206:209], v[174:177], v[66:81]
	v_add_f32_e32 v1, v98, v99
	v_add_f32_e32 v1, v100, v1
	v_add_f32_e32 v1, v101, v1
	v_add_f32_e32 v1, v102, v1
	v_add_f32_e32 v1, v103, v1
	v_cvt_pk_bf16_f32 v158, v98, v99
	v_cvt_pk_bf16_f32 v159, v100, v101
	ds_read_b64_tr_b16 v[250:251], v216 offset:28672
	ds_read_b64_tr_b16 v[252:253], v216 offset:29184
	s_waitcnt lgkmcnt(10)
	v_mfma_f32_32x32x16_bf16 v[114:129], v[198:201], v[174:177], v[66:81]
	v_add_f32_e32 v1, v104, v1
	v_add_f32_e32 v1, v105, v1
	v_add_f32_e32 v1, v106, v1
	v_add_f32_e32 v1, v107, v1
	v_cvt_pk_bf16_f32 v160, v102, v103
	v_cvt_pk_bf16_f32 v161, v104, v105
	ds_read_b64_tr_b16 v[198:199], v216 offset:25600
	ds_read_b64_tr_b16 v[200:201], v216 offset:26112
	s_waitcnt lgkmcnt(11)
	v_mfma_f32_32x32x16_bf16 v[130:145], v[202:205], v[170:173], v[130:145]
	v_add_f32_e32 v1, v108, v1
	v_add_f32_e32 v1, v109, v1
	v_add_f32_e32 v1, v110, v1
	v_add_f32_e32 v1, v111, v1
	v_cvt_pk_bf16_f32 v154, v106, v107
	v_cvt_pk_bf16_f32 v155, v108, v109
	ds_read_b64_tr_b16 v[106:107], v216 offset:29696
	ds_read_b64_tr_b16 v[108:109], v216 offset:30208
	s_waitcnt lgkmcnt(12)
	v_mfma_f32_32x32x16_bf16 v[114:129], v[194:197], v[170:173], v[114:129]
	v_add_f32_e32 v1, v112, v1
	v_add_f32_e32 v1, v113, v1
	v_add_f32_e32 v1, v82, v1
	v_add_f32_e32 v1, v83, v1
	v_cvt_pk_bf16_f32 v156, v110, v111
	v_cvt_pk_bf16_f32 v157, v112, v113
	ds_read_b64_tr_b16 v[102:103], v216 offset:26624
	ds_read_b64_tr_b16 v[104:105], v216 offset:27136
	s_waitcnt lgkmcnt(13)
	v_mfma_f32_32x32x16_bf16 v[130:145], v[190:193], v[166:169], v[130:145]
	v_add_f32_e32 v1, v84, v1
	v_add_f32_e32 v1, v85, v1
	v_add_f32_e32 v1, v86, v1
	v_add_f32_e32 v1, v87, v1
	v_cvt_pk_bf16_f32 v150, v82, v83
	v_cvt_pk_bf16_f32 v151, v84, v85
	ds_read_b64_tr_b16 v[98:99], v216 offset:30720
	ds_read_b64_tr_b16 v[100:101], v216 offset:31232
	s_waitcnt lgkmcnt(14)
	v_mfma_f32_32x32x16_bf16 v[114:129], v[186:189], v[166:169], v[114:129]
	v_add_f32_e32 v1, v88, v1
	v_add_f32_e32 v1, v89, v1
	v_add_f32_e32 v1, v90, v1
	v_add_f32_e32 v1, v91, v1
	v_cvt_pk_bf16_f32 v152, v86, v87
	v_cvt_pk_bf16_f32 v153, v88, v89
	ds_read_b64_tr_b16 v[86:87], v216 offset:27648
	ds_read_b64_tr_b16 v[88:89], v216 offset:28160
	s_waitcnt lgkmcnt(14)
	v_mfma_f32_32x32x16_bf16 v[130:145], v[182:185], v[162:165], v[130:145]
	v_add_f32_e32 v1, v92, v1
	v_add_f32_e32 v1, v93, v1
	v_add_f32_e32 v1, v94, v1
	v_add_f32_e32 v1, v95, v1
	v_cvt_pk_bf16_f32 v146, v90, v91
	v_cvt_pk_bf16_f32 v147, v92, v93
	ds_read_b64_tr_b16 v[90:91], v216 offset:31744
	ds_read_b64_tr_b16 v[92:93], v216 offset:32256
	v_mfma_f32_32x32x16_bf16 v[114:129], v[178:181], v[162:165], v[114:129]
	v_add_f32_e32 v1, v96, v1
	v_add_f32_e32 v1, v97, v1
	v_cvt_pk_bf16_f32 v148, v94, v95
	v_cvt_pk_bf16_f32 v149, v96, v97
	s_add_i32 s4, s15, s55
	v_lshl_add_u64 v[82:83], v[212:213], 0, s[62:63]
	s_mov_b32 m0, s4
	s_nop 0
	global_load_lds_dwordx4 v[82:83], off
	s_lshl_b32 s4, s84, 1
	s_waitcnt lgkmcnt(14)
	v_mfma_f32_32x32x16_bf16 v[50:65], v[158:161], v[226:229], v[50:65]
	v_lshl_add_u64 v[82:83], v[214:215], 0, s[58:59]
	s_add_i32 s4, s4, s1
	s_mov_b32 m0, s4
	s_nop 0
	global_load_lds_dwordx4 v[82:83], off
	v_lshl_add_u64 v[82:83], v[214:215], 0, s[64:65]
	s_addk_i32 s4, 0x2000
	s_mov_b32 m0, s4
	s_nop 0
	global_load_lds_dwordx4 v[82:83], off
	ds_read_b64_tr_b16 v[206:207], v216 offset:32768
	ds_read_b64_tr_b16 v[208:209], v216 offset:33280
	s_waitcnt lgkmcnt(14)
	v_mfma_f32_32x32x16_bf16 v[34:49], v[158:161], v[250:253], v[34:49]
	ds_read_b64_tr_b16 v[110:111], v216 offset:36864
	ds_read_b64_tr_b16 v[112:113], v216 offset:37376
	s_waitcnt lgkmcnt(14)
	v_mfma_f32_32x32x16_bf16 v[50:65], v[154:157], v[198:201], v[50:65]
	ds_read_b64_tr_b16 v[94:95], v216 offset:33792
	ds_read_b64_tr_b16 v[96:97], v216 offset:34304
	v_max_f32_e32 v82, v130, v131
	v_max3_f32 v83, v132, v133, v115
	v_max3_f32 v82, v82, v114, v116
	v_max3_f32 v82, v82, v117, v134
	v_max3_f32 v83, v83, v136, v137
	v_max3_f32 v82, v82, v135, v118
	v_max3_f32 v83, v83, v120, v121
	v_max3_f32 v82, v82, v119, v138
	v_max3_f32 v83, v83, v140, v141
	v_max3_f32 v82, v82, v139, v122
	v_max3_f32 v83, v83, v124, v125
	v_max3_f32 v82, v82, v123, v142
	v_max3_f32 v83, v83, v144, v145
	v_max3_f32 v82, v82, v143, v126
	v_max3_f32 v83, v83, v128, v129
	v_max3_f32 v82, v82, v127, v83
	v_cmp_lt_f32_e32 vcc, s13, v82
	s_cmp_lg_u64 vcc, 0
	v_add_f32_e32 v1, v249, v1
	s_cselect_b64 s[86:87], -1, 0
	s_cbranch_vccnz .LBB0_1134

.LBB0_1129:
	s_add_i32 s4, s84, 0x2000
	s_cmpk_lg_i32 s84, 0x4000
	s_cselect_b32 s4, s4, 0
	s_lshl_b32 s8, s15, 1
	v_add_u32_e32 v226, s8, v247
	ds_read_b64_tr_b16 v[206:207], v226 offset:24576
	ds_read_b64_tr_b16 v[208:209], v226 offset:25088
	v_mfma_f32_32x32x16_bf16 v[98:113], v[82:85], v[174:177], v[66:81]
	v_add_f32_e32 v86, v130, v131
	v_add_f32_e32 v86, v132, v86
	v_add_f32_e32 v86, v133, v86
	v_add_f32_e32 v86, v134, v86
	v_add_f32_e32 v86, v135, v86
	v_cvt_pk_bf16_f32 v158, v130, v131
	v_cvt_pk_bf16_f32 v159, v132, v133
	ds_read_b64_tr_b16 v[250:251], v226 offset:28672
	ds_read_b64_tr_b16 v[252:253], v226 offset:29184
	v_add_f32_e32 v82, v136, v86
	v_add_f32_e32 v82, v137, v82
	v_add_f32_e32 v82, v138, v82
	v_add_f32_e32 v130, v139, v82
	v_mfma_f32_32x32x16_bf16 v[82:97], v[198:201], v[174:177], v[66:81]
	v_cvt_pk_bf16_f32 v160, v134, v135
	v_cvt_pk_bf16_f32 v161, v136, v137
	ds_read_b64_tr_b16 v[198:199], v226 offset:25600
	ds_read_b64_tr_b16 v[200:201], v226 offset:26112
	v_mfma_f32_32x32x16_bf16 v[98:113], v[202:205], v[170:173], v[98:113]
	v_add_f32_e32 v130, v140, v130
	v_add_f32_e32 v130, v141, v130
	v_add_f32_e32 v130, v142, v130
	v_add_f32_e32 v130, v143, v130
	v_cvt_pk_bf16_f32 v154, v138, v139
	v_cvt_pk_bf16_f32 v155, v140, v141
	ds_read_b64_tr_b16 v[138:139], v226 offset:29696
	ds_read_b64_tr_b16 v[140:141], v226 offset:30208
	v_mfma_f32_32x32x16_bf16 v[82:97], v[190:193], v[170:173], v[82:97]
	v_add_f32_e32 v130, v144, v130
	v_add_f32_e32 v130, v145, v130
	v_add_f32_e32 v130, v114, v130
	v_add_f32_e32 v130, v115, v130
	v_cvt_pk_bf16_f32 v156, v142, v143
	v_cvt_pk_bf16_f32 v157, v144, v145
	ds_read_b64_tr_b16 v[134:135], v226 offset:26624
	ds_read_b64_tr_b16 v[136:137], v226 offset:27136
	v_mfma_f32_32x32x16_bf16 v[98:113], v[194:197], v[166:169], v[98:113]
	v_add_f32_e32 v130, v116, v130
	v_add_f32_e32 v130, v117, v130
	v_add_f32_e32 v130, v118, v130
	v_add_f32_e32 v142, v119, v130
	v_cvt_pk_bf16_f32 v150, v114, v115
	v_cvt_pk_bf16_f32 v151, v116, v117
	ds_read_b64_tr_b16 v[130:131], v226 offset:30720
	ds_read_b64_tr_b16 v[132:133], v226 offset:31232
	v_mfma_f32_32x32x16_bf16 v[82:97], v[182:185], v[166:169], v[82:97]
	v_add_f32_e32 v114, v120, v142
	v_add_f32_e32 v114, v121, v114
	v_add_f32_e32 v114, v122, v114
	v_add_f32_e32 v142, v123, v114
	v_cvt_pk_bf16_f32 v152, v118, v119
	v_cvt_pk_bf16_f32 v153, v120, v121
	ds_read_b64_tr_b16 v[114:115], v226 offset:27648
	ds_read_b64_tr_b16 v[116:117], v226 offset:28160
	v_mfma_f32_32x32x16_bf16 v[98:113], v[186:189], v[162:165], v[98:113]
	v_add_f32_e32 v118, v124, v142
	v_add_f32_e32 v118, v125, v118
	v_add_f32_e32 v118, v126, v118
	v_add_f32_e32 v142, v127, v118
	v_cvt_pk_bf16_f32 v146, v122, v123
	v_cvt_pk_bf16_f32 v147, v124, v125
	ds_read_b64_tr_b16 v[118:119], v226 offset:31744
	ds_read_b64_tr_b16 v[120:121], v226 offset:32256
	v_mfma_f32_32x32x16_bf16 v[82:97], v[178:181], v[162:165], v[82:97]
	v_add_f32_e32 v122, v128, v142
	v_add_f32_e32 v122, v129, v122
	v_add_f32_e32 v178, 0, v122
	v_cvt_pk_bf16_f32 v148, v126, v127
	v_cvt_pk_bf16_f32 v149, v128, v129
	s_mov_b64 s[8:9], 0x180000
	v_lshl_add_u64 v[122:123], v[212:213], 0, s[8:9]
	s_add_i32 s8, s84, s55
	s_mov_b32 m0, s8
	s_nop 0
	global_load_lds_dwordx4 v[122:123], off
	s_lshl_b32 s8, s4, 1
	s_waitcnt lgkmcnt(14)
	v_mfma_f32_32x32x16_bf16 v[50:65], v[158:161], v[206:209], v[50:65]
	v_lshl_add_u64 v[216:217], v[214:215], 0, s[60:61]
	s_add_i32 s8, s8, s1
	s_mov_b32 m0, s8
	s_nop 0
	global_load_lds_dwordx4 v[216:217], off
	v_lshl_add_u64 v[122:123], v[214:215], 0, s[66:67]
	s_addk_i32 s8, 0x2000
	s_mov_b32 m0, s8
	s_nop 0
	global_load_lds_dwordx4 v[122:123], off
	ds_read_b64_tr_b16 v[142:143], v226 offset:32768
	ds_read_b64_tr_b16 v[144:145], v226 offset:33280
	s_waitcnt lgkmcnt(14)
	v_mfma_f32_32x32x16_bf16 v[34:49], v[158:161], v[250:253], v[34:49]
	ds_read_b64_tr_b16 v[126:127], v226 offset:36864
	ds_read_b64_tr_b16 v[128:129], v226 offset:37376
	s_waitcnt lgkmcnt(14)
	v_mfma_f32_32x32x16_bf16 v[50:65], v[154:157], v[198:201], v[50:65]
	ds_read_b64_tr_b16 v[122:123], v226 offset:33792
	ds_read_b64_tr_b16 v[124:125], v226 offset:34304
	v_max_f32_e32 v179, v98, v99
	v_max3_f32 v180, v100, v101, v83
	v_max3_f32 v179, v179, v82, v84
	v_max3_f32 v179, v179, v85, v102
	v_max3_f32 v180, v180, v104, v105
	v_max3_f32 v179, v179, v103, v86
	v_max3_f32 v180, v180, v88, v89
	v_max3_f32 v179, v179, v87, v106
	v_max3_f32 v180, v180, v108, v109
	v_max3_f32 v179, v179, v107, v90
	v_max3_f32 v180, v180, v92, v93
	v_max3_f32 v179, v179, v91, v110
	v_max3_f32 v180, v180, v112, v113
	v_max3_f32 v179, v179, v111, v94
	v_max3_f32 v180, v180, v96, v97
	v_add_f32_e32 v249, v1, v178
	v_max3_f32 v1, v179, v95, v180
	v_cmp_lt_f32_e32 vcc, s13, v1
	s_cmp_lg_u64 vcc, 0
	s_cselect_b64 s[86:87], -1, 0
	s_cbranch_vccnz .LBB0_1137

;   #define RESC() do{ if(resc){ asm volatile("s_waitcnt lgkmcnt(0)":::"memory"); \
;       _Pragma("unroll") for(int d_=0;d_<ND;++d_) _Pragma("unroll") for(int r=0;r<16;++r)o[d_][r]*=wsf[crow(r,hi)]; } }while(0)
;   #define ROT() do{sl_prev=sl_cur;sl_cur=sl_next;sl_next=(sl_next==(NSLOT-1)*SLOTB)?0:sl_next+SLOTB;}while(0)
;   #define ENDW(tt) do{ if((tt)+3<NT){ if(MODE==2){WAIT_BAR(3);}else{WAIT_BAR(2);} } else if((tt)+2<NT){ if(MODE==2){WAIT_BAR(2);}else{WAIT_BAR(1);} } else {WAIT_BAR(0);} }while(0)
; template<int MODE,int THRL> __device__ __forceinline__ void attn_unit(const bf16*Qw0,int PQ,const bf16*__restrict__ Kh,int PK,const bf16*__restrict__ Vh,int PV,bf16*Ow0,int PO,int NT,int nabase,int nar0,const float*rpbh,char*shm,int&rot,bool pre,bool hasn,long dKn,long dVn){
;     ...
;   for(;t+1<NT;t+=2){
;     STEP(pB0,pB1,pA0,pA1,t,(t+3<NT),(t+1<NT),(t+1<NT));       ENDW(t);   RESC(); ROT();
;     STEP(pA0,pA1,pB0,pB1,t+1,(t+4<NT),(t+2<NT),(t+2<NT));     ENDW(t+1); RESC(); ROT();
.LBB0_1141:
	s_lshl_b32 s9, s84, 1
	v_add_u32_e32 v250, s9, v247
	ds_read_b64_tr_b16 v[210:211], v250 offset:24576
	ds_read_b64_tr_b16 v[212:213], v250 offset:25088
	v_mfma_f32_32x32x16_bf16 v[130:145], v[206:209], v[174:177], v[66:81]
	v_add_f32_e32 v1, v98, v99
	v_add_f32_e32 v1, v100, v1
	v_add_f32_e32 v1, v101, v1
	v_add_f32_e32 v1, v102, v1
	v_add_f32_e32 v1, v103, v1
	v_cvt_pk_bf16_f32 v158, v98, v99
	v_cvt_pk_bf16_f32 v159, v100, v101
	ds_read_b64_tr_b16 v[214:215], v250 offset:28672
	ds_read_b64_tr_b16 v[216:217], v250 offset:29184
	v_mfma_f32_32x32x16_bf16 v[114:129], v[198:201], v[174:177], v[66:81]
	v_add_f32_e32 v1, v104, v1
	v_add_f32_e32 v1, v105, v1
	v_add_f32_e32 v1, v106, v1
	v_add_f32_e32 v1, v107, v1
	v_cvt_pk_bf16_f32 v160, v102, v103
	v_cvt_pk_bf16_f32 v161, v104, v105
	ds_read_b64_tr_b16 v[198:199], v250 offset:25600
	ds_read_b64_tr_b16 v[200:201], v250 offset:26112
	v_mfma_f32_32x32x16_bf16 v[130:145], v[202:205], v[170:173], v[130:145]
	v_add_f32_e32 v1, v108, v1
	v_add_f32_e32 v1, v109, v1
	v_add_f32_e32 v1, v110, v1
	v_add_f32_e32 v1, v111, v1
	v_cvt_pk_bf16_f32 v154, v106, v107
	v_cvt_pk_bf16_f32 v155, v108, v109
	ds_read_b64_tr_b16 v[106:107], v250 offset:29696
	ds_read_b64_tr_b16 v[108:109], v250 offset:30208
	v_mfma_f32_32x32x16_bf16 v[114:129], v[194:197], v[170:173], v[114:129]
	v_add_f32_e32 v1, v112, v1
	v_add_f32_e32 v1, v113, v1
	v_add_f32_e32 v1, v82, v1
	v_add_f32_e32 v1, v83, v1
	v_cvt_pk_bf16_f32 v156, v110, v111
	v_cvt_pk_bf16_f32 v157, v112, v113
	ds_read_b64_tr_b16 v[102:103], v250 offset:26624
	ds_read_b64_tr_b16 v[104:105], v250 offset:27136
	v_mfma_f32_32x32x16_bf16 v[130:145], v[190:193], v[166:169], v[130:145]
	v_add_f32_e32 v1, v84, v1
	v_add_f32_e32 v1, v85, v1
	v_add_f32_e32 v1, v86, v1
	v_add_f32_e32 v1, v87, v1
	v_cvt_pk_bf16_f32 v150, v82, v83
	v_cvt_pk_bf16_f32 v151, v84, v85
	ds_read_b64_tr_b16 v[98:99], v250 offset:30720
	ds_read_b64_tr_b16 v[100:101], v250 offset:31232
	v_mfma_f32_32x32x16_bf16 v[114:129], v[186:189], v[166:169], v[114:129]
	v_add_f32_e32 v1, v88, v1
	v_add_f32_e32 v1, v89, v1
	v_add_f32_e32 v1, v90, v1
	v_add_f32_e32 v1, v91, v1
	v_cvt_pk_bf16_f32 v152, v86, v87
	v_cvt_pk_bf16_f32 v153, v88, v89
	ds_read_b64_tr_b16 v[86:87], v250 offset:27648
	ds_read_b64_tr_b16 v[88:89], v250 offset:28160
	v_mfma_f32_32x32x16_bf16 v[130:145], v[182:185], v[162:165], v[130:145]
	v_add_f32_e32 v1, v92, v1
	v_add_f32_e32 v1, v93, v1
	v_add_f32_e32 v1, v94, v1
	v_add_f32_e32 v1, v95, v1
	v_cvt_pk_bf16_f32 v146, v90, v91
	v_cvt_pk_bf16_f32 v147, v92, v93
	ds_read_b64_tr_b16 v[90:91], v250 offset:31744
	ds_read_b64_tr_b16 v[92:93], v250 offset:32256
	v_mfma_f32_32x32x16_bf16 v[114:129], v[178:181], v[162:165], v[114:129]
	v_add_f32_e32 v1, v96, v1
	v_add_f32_e32 v1, v97, v1
	v_cvt_pk_bf16_f32 v148, v94, v95
	v_cvt_pk_bf16_f32 v149, v96, v97
	s_cmpk_gt_u32 s15, 0x80
	s_cselect_b64 s[88:89], -1, 0
	s_and_b64 vcc, exec, s[88:89]
	s_mov_b64 s[90:91], s[86:87]
	s_cbranch_vccnz .LBB0_1143
	s_add_i32 s9, s4, s55
	v_lshl_add_u64 v[82:83], v[226:227], 0, s[62:63]
	s_mov_b32 m0, s9
	s_nop 0
	global_load_lds_dwordx4 v[82:83], off
	s_mul_i32 s84, s15, 0x30000
	s_mov_b64 s[90:91], s[84:85]
.LBB0_1143:
	v_lshl_add_u64 v[228:229], s[90:91], 1, v[224:225]
	s_lshl_b32 s33, s8, 1
	s_waitcnt lgkmcnt(14)
	v_mfma_f32_32x32x16_bf16 v[50:65], v[158:161], v[210:213], v[50:65]
	v_lshl_add_u64 v[82:83], v[228:229], 0, s[58:59]
	s_add_i32 s9, s33, s1
	s_mov_b32 m0, s9
	s_nop 0
	global_load_lds_dwordx4 v[82:83], off
	v_lshl_add_u64 v[82:83], v[228:229], 0, s[64:65]
	s_addk_i32 s9, 0x2000
	s_mov_b32 m0, s9
	s_nop 0
	global_load_lds_dwordx4 v[82:83], off
	ds_read_b64_tr_b16 v[206:207], v250 offset:32768
	ds_read_b64_tr_b16 v[208:209], v250 offset:33280
	v_add_f32_e32 v1, v249, v1
	s_waitcnt lgkmcnt(14)
	v_mfma_f32_32x32x16_bf16 v[34:49], v[158:161], v[214:217], v[34:49]
	ds_read_b64_tr_b16 v[110:111], v250 offset:36864
	ds_read_b64_tr_b16 v[112:113], v250 offset:37376
	s_waitcnt lgkmcnt(14)
	v_mfma_f32_32x32x16_bf16 v[50:65], v[154:157], v[198:201], v[50:65]
	ds_read_b64_tr_b16 v[94:95], v250 offset:33792
	ds_read_b64_tr_b16 v[96:97], v250 offset:34304
	v_max_f32_e32 v82, v130, v131
	v_max3_f32 v83, v132, v133, v115
	v_max3_f32 v82, v82, v114, v116
	v_max3_f32 v82, v82, v117, v134
	v_max3_f32 v83, v83, v136, v137
	v_max3_f32 v82, v82, v135, v118
	v_max3_f32 v83, v83, v120, v121
	v_max3_f32 v82, v82, v119, v138
	v_max3_f32 v83, v83, v140, v141
	v_max3_f32 v82, v82, v139, v122
	v_max3_f32 v83, v83, v124, v125
	v_max3_f32 v82, v82, v123, v142
	v_max3_f32 v83, v83, v144, v145
	v_max3_f32 v82, v82, v143, v126
	v_max3_f32 v83, v83, v128, v129
	v_max3_f32 v82, v82, v127, v83
	v_mov_b32_e32 v83, v82
	s_nop 1
	v_permlane32_swap_b32_e32 v82, v83
	v_max_f32_e32 v82, v82, v83
	v_cmp_lt_f32_e32 vcc, s13, v82
	s_cmp_lg_u64 vcc, 0
	s_cselect_b64 s[92:93], -1, 0
	s_cbranch_vccnz .LBB0_1161

;   #define RESC() do{ if(resc){ asm volatile("s_waitcnt lgkmcnt(0)":::"memory"); \
;       _Pragma("unroll") for(int d_=0;d_<ND;++d_) _Pragma("unroll") for(int r=0;r<16;++r)o[d_][r]*=wsf[crow(r,hi)]; } }while(0)
;   #define ROT() do{sl_prev=sl_cur;sl_cur=sl_next;sl_next=(sl_next==(NSLOT-1)*SLOTB)?0:sl_next+SLOTB;}while(0)
;   #define ENDW(tt) do{ if((tt)+3<NT){ if(MODE==2){WAIT_BAR(3);}else{WAIT_BAR(2);} } else if((tt)+2<NT){ if(MODE==2){WAIT_BAR(2);}else{WAIT_BAR(1);} } else {WAIT_BAR(0);} }while(0)
; template<int MODE,int THRL> __device__ __forceinline__ void attn_unit(const bf16*Qw0,int PQ,const bf16*__restrict__ Kh,int PK,const bf16*__restrict__ Vh,int PV,bf16*Ow0,int PO,int NT,int nabase,int nar0,const float*rpbh,char*shm,int&rot,bool pre,bool hasn,long dKn,long dVn){
;     ...
;   for(;t+1<NT;t+=2){
;     STEP(pB0,pB1,pA0,pA1,t,(t+3<NT),(t+1<NT),(t+1<NT));       ENDW(t);   RESC(); ROT();
;     STEP(pA0,pA1,pB0,pB1,t+1,(t+4<NT),(t+2<NT),(t+2<NT));     ENDW(t+1); RESC(); ROT();
.LBB0_1148:
	s_lshl_b32 s4, s4, 1
	v_add_u32_e32 v214, s4, v247
	ds_read_b64_tr_b16 v[206:207], v214 offset:24576
	ds_read_b64_tr_b16 v[208:209], v214 offset:25088
	v_mfma_f32_32x32x16_bf16 v[98:113], v[82:85], v[174:177], v[66:81]
	v_add_f32_e32 v86, v130, v131
	v_add_f32_e32 v86, v132, v86
	v_add_f32_e32 v86, v133, v86
	v_add_f32_e32 v86, v134, v86
	v_add_f32_e32 v86, v135, v86
	v_cvt_pk_bf16_f32 v158, v130, v131
	v_cvt_pk_bf16_f32 v159, v132, v133
	ds_read_b64_tr_b16 v[210:211], v214 offset:28672
	ds_read_b64_tr_b16 v[212:213], v214 offset:29184
	v_add_f32_e32 v82, v136, v86
	v_add_f32_e32 v82, v137, v82
	v_add_f32_e32 v82, v138, v82
	v_add_f32_e32 v130, v139, v82
	v_mfma_f32_32x32x16_bf16 v[82:97], v[198:201], v[174:177], v[66:81]
	v_cvt_pk_bf16_f32 v160, v134, v135
	v_cvt_pk_bf16_f32 v161, v136, v137
	ds_read_b64_tr_b16 v[198:199], v214 offset:25600
	ds_read_b64_tr_b16 v[200:201], v214 offset:26112
	v_mfma_f32_32x32x16_bf16 v[98:113], v[202:205], v[170:173], v[98:113]
	v_add_f32_e32 v130, v140, v130
	v_add_f32_e32 v130, v141, v130
	v_add_f32_e32 v130, v142, v130
	v_add_f32_e32 v130, v143, v130
	v_cvt_pk_bf16_f32 v154, v138, v139
	v_cvt_pk_bf16_f32 v155, v140, v141
	ds_read_b64_tr_b16 v[138:139], v214 offset:29696
	ds_read_b64_tr_b16 v[140:141], v214 offset:30208
	v_mfma_f32_32x32x16_bf16 v[82:97], v[190:193], v[170:173], v[82:97]
	v_add_f32_e32 v130, v144, v130
	v_add_f32_e32 v130, v145, v130
	v_add_f32_e32 v130, v114, v130
	v_add_f32_e32 v130, v115, v130
	v_cvt_pk_bf16_f32 v156, v142, v143
	v_cvt_pk_bf16_f32 v157, v144, v145
	ds_read_b64_tr_b16 v[134:135], v214 offset:26624
	ds_read_b64_tr_b16 v[136:137], v214 offset:27136
	v_mfma_f32_32x32x16_bf16 v[98:113], v[194:197], v[166:169], v[98:113]
	v_add_f32_e32 v130, v116, v130
	v_add_f32_e32 v130, v117, v130
	v_add_f32_e32 v130, v118, v130
	v_add_f32_e32 v142, v119, v130
	v_cvt_pk_bf16_f32 v150, v114, v115
	v_cvt_pk_bf16_f32 v151, v116, v117
	ds_read_b64_tr_b16 v[130:131], v214 offset:30720
	ds_read_b64_tr_b16 v[132:133], v214 offset:31232
	v_mfma_f32_32x32x16_bf16 v[82:97], v[182:185], v[166:169], v[82:97]
	v_add_f32_e32 v114, v120, v142
	v_add_f32_e32 v114, v121, v114
	v_add_f32_e32 v114, v122, v114
	v_add_f32_e32 v142, v123, v114
	v_cvt_pk_bf16_f32 v152, v118, v119
	v_cvt_pk_bf16_f32 v153, v120, v121
	ds_read_b64_tr_b16 v[114:115], v214 offset:27648
	ds_read_b64_tr_b16 v[116:117], v214 offset:28160
	v_mfma_f32_32x32x16_bf16 v[98:113], v[186:189], v[162:165], v[98:113]
	v_add_f32_e32 v118, v124, v142
	v_add_f32_e32 v118, v125, v118
	v_add_f32_e32 v118, v126, v118
	v_add_f32_e32 v142, v127, v118
	v_cvt_pk_bf16_f32 v146, v122, v123
	v_cvt_pk_bf16_f32 v147, v124, v125
	ds_read_b64_tr_b16 v[118:119], v214 offset:31744
	ds_read_b64_tr_b16 v[120:121], v214 offset:32256
	v_mfma_f32_32x32x16_bf16 v[82:97], v[178:181], v[162:165], v[82:97]
	v_add_f32_e32 v122, v128, v142
	v_add_f32_e32 v122, v129, v122
	v_cvt_pk_bf16_f32 v148, v126, v127
	v_cvt_pk_bf16_f32 v149, v128, v129
	s_cmpk_gt_u32 s15, 0x7f
	s_cselect_b64 s[92:93], -1, 0
	s_and_b64 vcc, exec, s[92:93]
	s_cbranch_vccnz .LBB0_1150
	v_lshl_add_u64 v[124:125], s[90:91], 1, v[220:221]
	s_mov_b64 s[90:91], 0x180800
	s_add_i32 s4, s8, s55
	v_lshl_add_u64 v[124:125], v[124:125], 0, s[90:91]
	s_mov_b32 m0, s4
	s_nop 0
	global_load_lds_dwordx4 v[124:125], off
.LBB0_1150:
	s_add_i32 s4, s8, 0x2000
	s_cmpk_lg_i32 s8, 0x4000
	s_cselect_b32 s4, s4, 0
	s_lshl_b32 s84, s4, 1
	s_waitcnt lgkmcnt(14)
	v_mfma_f32_32x32x16_bf16 v[50:65], v[158:161], v[206:209], v[50:65]
	s_add_i32 s9, s84, s1
	v_lshl_add_u64 v[124:125], v[228:229], 0, s[60:61]
	s_mov_b32 m0, s9
	s_nop 0
	global_load_lds_dwordx4 v[124:125], off
	v_add_f32_e32 v249, v1, v122
	v_lshl_add_u64 v[122:123], v[228:229], 0, s[66:67]
	s_addk_i32 s9, 0x2000
	s_mov_b32 m0, s9
	s_nop 0
	global_load_lds_dwordx4 v[122:123], off
	ds_read_b64_tr_b16 v[142:143], v214 offset:32768
	ds_read_b64_tr_b16 v[144:145], v214 offset:33280
	s_waitcnt lgkmcnt(14)
	v_mfma_f32_32x32x16_bf16 v[34:49], v[158:161], v[210:213], v[34:49]
	ds_read_b64_tr_b16 v[126:127], v214 offset:36864
	ds_read_b64_tr_b16 v[128:129], v214 offset:37376
	s_waitcnt lgkmcnt(14)
	v_mfma_f32_32x32x16_bf16 v[50:65], v[154:157], v[198:201], v[50:65]
	ds_read_b64_tr_b16 v[122:123], v214 offset:33792
	ds_read_b64_tr_b16 v[124:125], v214 offset:34304
	v_max_f32_e32 v1, v98, v99
	v_max3_f32 v178, v100, v101, v83
	v_max3_f32 v1, v1, v82, v84
	v_max3_f32 v1, v1, v85, v102
	v_max3_f32 v178, v178, v104, v105
	v_max3_f32 v1, v1, v103, v86
	v_max3_f32 v178, v178, v88, v89
	v_max3_f32 v1, v1, v87, v106
	v_max3_f32 v178, v178, v108, v109
	v_max3_f32 v1, v1, v107, v90
	v_max3_f32 v178, v178, v92, v93
	v_max3_f32 v1, v1, v91, v110
	v_max3_f32 v178, v178, v112, v113
	v_max3_f32 v1, v1, v111, v94
	v_max3_f32 v178, v178, v96, v97
	v_max3_f32 v1, v1, v95, v178
	v_mov_b32_e32 v178, v1
	s_nop 1
	v_permlane32_swap_b32_e32 v1, v178
	v_max_f32_e32 v1, v1, v178
	v_cmp_lt_f32_e32 vcc, s13, v1
	s_cmp_lg_u64 vcc, 0
	s_cselect_b64 s[90:91], -1, 0
	s_cbranch_vccnz .LBB0_1164

; template <int l> __device__ __forceinline__ void layer_body(const Args& a, unsigned char* lds, const XcdBarrier& bar, int G, int bx, int vcu, int gw, int NGW, int lane_, int tid_k, int wave) {
;     ...
;                     int g; bool ok = true; if (G == 256) g = (((vcu >> 5) * 4 + (i >> 1)) << 6) + (i & 1) * 32 + (vcu & 31); else { g = i * G + vcu; ok = g < nun; }
;                     int g2; bool ok2 = (i + 1 < per); if (G == 256) g2 = (((vcu >> 5) * 4 + ((i + 1) >> 1)) << 6) + ((i + 1) & 1) * 32 + (vcu & 31); else { g2 = (i + 1) * G + vcu; ok2 = ok2 && g2 < nun; }
;                     if (!ok2) g2 = g;
;                     const int bh2 = g2 >> 6, b2 = bh2 >> 3, h2 = bh2 & 7, map2 = (g2 & 63) >> 5; const size_t rb2 = (size_t)b2 * TPB;
;                     if (!ok) pre = false;
;                     if (ok) { const int bh = g >> 6, b = bh >> 3, h = bh & 7, sub = g & 63, map = sub >> 5, qb = sub & 31;
;                         const size_t rb = (size_t)b * TPB, rq = rb + CTXL + (size_t)qb * 256;
;                         attn_body::attn_unit<2, 8>(qkv + rq * DIFF_IN + h * 128 + map * 64, DIFF_IN, qkv + rb * DIFF_IN + 1024 + h * 128 + map * 64, DIFF_IN, qkv + rb * DIFF_IN + 2048 + h * 128, DIFF_IN,
;                                                    (abf*)OP + ((size_t)b * SEQ + (size_t)qb * 256) * 2048 + map * 1024 + h * 128, 2048, TPB / 64, 0, 0, nullptr, (char*)lds,
;                                                    rot, pre, ok2, (long)(rb2 * DIFF_IN + h2 * 128 + map2 * 64) - (long)(rb * DIFF_IN + h * 128 + map * 64), (long)(rb2 * DIFF_IN + h2 * 128) - (long)(rb * DIFF_IN + h * 128));
.LBB0_1167:
	v_add_u32_e32 v210, s33, v247
	ds_read_b64_tr_b16 v[134:135], v210 offset:24576
	ds_read_b64_tr_b16 v[136:137], v210 offset:25088
	v_mfma_f32_32x32x16_bf16 v[114:129], v[206:209], v[174:177], v[66:81]
	v_add_f32_e32 v1, v98, v99
	v_add_f32_e32 v1, v100, v1
	v_add_f32_e32 v1, v101, v1
	v_add_f32_e32 v1, v102, v1
	v_add_f32_e32 v1, v103, v1
	v_cvt_pk_bf16_f32 v158, v98, v99
	v_cvt_pk_bf16_f32 v159, v100, v101
	ds_read_b64_tr_b16 v[206:207], v210 offset:28672
	ds_read_b64_tr_b16 v[208:209], v210 offset:29184
	v_mfma_f32_32x32x16_bf16 v[66:81], v[198:201], v[174:177], v[66:81]
	v_add_f32_e32 v1, v104, v1
	v_add_f32_e32 v1, v105, v1
	v_add_f32_e32 v1, v106, v1
	v_add_f32_e32 v1, v107, v1
	v_cvt_pk_bf16_f32 v160, v102, v103
	v_cvt_pk_bf16_f32 v161, v104, v105
	ds_read_b64_tr_b16 v[174:175], v210 offset:25600
	ds_read_b64_tr_b16 v[176:177], v210 offset:26112
	v_mfma_f32_32x32x16_bf16 v[114:129], v[202:205], v[170:173], v[114:129]
	v_add_f32_e32 v1, v108, v1
	v_add_f32_e32 v1, v109, v1
	v_add_f32_e32 v1, v110, v1
	v_add_f32_e32 v1, v111, v1
	v_cvt_pk_bf16_f32 v154, v106, v107
	v_cvt_pk_bf16_f32 v155, v108, v109
	ds_read_b64_tr_b16 v[98:99], v210 offset:29696
	ds_read_b64_tr_b16 v[100:101], v210 offset:30208
	v_mfma_f32_32x32x16_bf16 v[66:81], v[194:197], v[170:173], v[66:81]
	v_add_f32_e32 v1, v112, v1
	v_add_f32_e32 v1, v113, v1
	v_add_f32_e32 v1, v82, v1
	v_add_f32_e32 v1, v83, v1
	v_cvt_pk_bf16_f32 v156, v110, v111
	v_cvt_pk_bf16_f32 v157, v112, v113
	ds_read_b64_tr_b16 v[102:103], v210 offset:26624
	ds_read_b64_tr_b16 v[104:105], v210 offset:27136
	v_mfma_f32_32x32x16_bf16 v[114:129], v[190:193], v[166:169], v[114:129]
	v_add_f32_e32 v1, v84, v1
	v_add_f32_e32 v1, v85, v1
	v_add_f32_e32 v1, v86, v1
	v_add_f32_e32 v1, v87, v1
	v_cvt_pk_bf16_f32 v150, v82, v83
	v_cvt_pk_bf16_f32 v151, v84, v85
	ds_read_b64_tr_b16 v[106:107], v210 offset:30720
	ds_read_b64_tr_b16 v[108:109], v210 offset:31232
	v_mfma_f32_32x32x16_bf16 v[66:81], v[186:189], v[166:169], v[66:81]
	v_add_f32_e32 v1, v88, v1
	v_add_f32_e32 v1, v89, v1
	v_add_f32_e32 v1, v90, v1
	v_add_f32_e32 v1, v91, v1
	v_cvt_pk_bf16_f32 v152, v86, v87
	v_cvt_pk_bf16_f32 v153, v88, v89
	ds_read_b64_tr_b16 v[110:111], v210 offset:27648
	ds_read_b64_tr_b16 v[112:113], v210 offset:28160
	v_mfma_f32_32x32x16_bf16 v[114:129], v[182:185], v[162:165], v[114:129]
	v_add_f32_e32 v1, v92, v1
	v_add_f32_e32 v1, v93, v1
	v_add_f32_e32 v1, v94, v1
	v_add_f32_e32 v1, v95, v1
	v_cvt_pk_bf16_f32 v146, v90, v91
	v_cvt_pk_bf16_f32 v147, v92, v93
	ds_read_b64_tr_b16 v[130:131], v210 offset:31744
	ds_read_b64_tr_b16 v[132:133], v210 offset:32256
	v_mfma_f32_32x32x16_bf16 v[66:81], v[178:181], v[162:165], v[66:81]
	v_add_f32_e32 v1, v96, v1
	v_add_f32_e32 v1, v97, v1
	v_cvt_pk_bf16_f32 v148, v94, v95
	v_cvt_pk_bf16_f32 v149, v96, v97
	s_andn2_b64 vcc, exec, s[68:69]
	s_cbranch_vccnz .LBB0_1169
	s_and_b64 s[86:87], s[68:69], exec
	s_cselect_b32 s15, s54, s96
	s_ashr_i32 s33, s15, 9
	s_lshl_b32 s15, s15, 1
	s_mul_hi_i32 s87, s33, 0x18c0000
	s_mul_i32 s33, s33, 0x18c0000
	s_and_b32 s54, s15, 0x380
	s_or_b64 s[80:81], s[82:83], s[80:81]
	s_or_b32 s86, s33, s54
	s_and_b32 s15, s15, 64
	s_or_b64 s[10:11], s[80:81], s[10:11]
	s_sub_u32 s10, s15, s10
	s_subb_u32 s11, 0, s11
	v_lshl_add_u64 v[82:83], s[10:11], 1, v[220:221]
	s_sub_u32 s80, s86, s80
	v_lshl_add_u64 v[82:83], s[86:87], 1, v[82:83]
	s_mov_b64 s[10:11], 0x800
	s_subb_u32 s81, s87, s81
	v_lshl_add_u64 v[84:85], v[82:83], 0, s[10:11]
	s_add_i32 s10, s9, s55
	s_mov_b32 m0, s10
	s_nop 0
	global_load_lds_dwordx4 v[84:85], off
	s_lshl_b32 s10, s9, 1
	v_lshl_add_u64 v[86:87], s[80:81], 1, v[224:225]
	s_add_i32 s1, s10, s1
	s_mov_b32 m0, s1
	s_nop 0
	global_load_lds_dwordx4 v[86:87], off
	s_mov_b64 s[10:11], 0x80
	v_lshl_add_u64 v[84:85], v[86:87], 0, s[10:11]
	s_addk_i32 s1, 0x2000
	s_mov_b32 m0, s1
	s_nop 0
	global_load_lds_dwordx4 v[84:85], off
	s_mov_b64 s[10:11], 0x60800
	v_lshl_add_u64 v[84:85], v[82:83], 0, s[10:11]
	s_add_i32 s1, s8, s55
	s_mov_b32 m0, s1
	s_nop 0
	global_load_lds_dwordx4 v[84:85], off
	s_mov_b64 s[10:11], 0xc0800
	v_lshl_add_u64 v[82:83], v[82:83], 0, s[10:11]
	s_add_i32 s1, s4, s55
	s_mov_b32 m0, s1
	s_nop 0
	global_load_lds_dwordx4 v[82:83], off
